# attention PV operands swapped (O transposed: lane = query row): rescale and 1/l become per-lane scalars, O epilogue via permlane32_swap + direct 16B stores, no LDS staging
# speedup vs baseline: 1.1478x; 1.0010x over previous
.Lat_mainloop:
.Lat_step_M1:
	v_add_u32_e32 v243, s16, v204
	ds_read_b64_tr_b16 v[214:215], v243 offset:24576
	ds_read_b64_tr_b16 v[216:217], v243 offset:25088
	v_mfma_f32_32x32x16_bf16 v[112:127], v[176:179], v[144:147], v[64:79]
	v_add_f32_e32 v245, v80, v81
	v_add_f32_e32 v245, v82, v245
	v_add_f32_e32 v245, v83, v245
	v_add_f32_e32 v245, v84, v245
	v_add_f32_e32 v245, v85, v245
	v_cvt_pk_bf16_f32 v160, v80, v81
	v_cvt_pk_bf16_f32 v161, v82, v83
	ds_read_b64_tr_b16 v[80:81], v243 offset:28672
	ds_read_b64_tr_b16 v[82:83], v243 offset:29184
	v_mfma_f32_32x32x16_bf16 v[128:143], v[180:183], v[144:147], v[64:79]
	v_add_f32_e32 v245, v86, v245
	v_add_f32_e32 v245, v87, v245
	v_add_f32_e32 v245, v88, v245
	v_add_f32_e32 v245, v89, v245
	v_cvt_pk_bf16_f32 v162, v84, v85
	v_cvt_pk_bf16_f32 v163, v86, v87
	ds_read_b64_tr_b16 v[84:85], v243 offset:25600
	ds_read_b64_tr_b16 v[86:87], v243 offset:26112
	v_mfma_f32_32x32x16_bf16 v[112:127], v[184:187], v[148:151], v[112:127]
	v_add_f32_e32 v245, v90, v245
	v_add_f32_e32 v245, v91, v245
	v_add_f32_e32 v245, v92, v245
	v_add_f32_e32 v245, v93, v245
	v_cvt_pk_bf16_f32 v164, v88, v89
	v_cvt_pk_bf16_f32 v165, v90, v91
	ds_read_b64_tr_b16 v[88:89], v243 offset:29696
	ds_read_b64_tr_b16 v[90:91], v243 offset:30208
	v_mfma_f32_32x32x16_bf16 v[128:143], v[188:191], v[148:151], v[128:143]
	v_add_f32_e32 v245, v94, v245
	v_add_f32_e32 v245, v95, v245
	v_add_f32_e32 v245, v96, v245
	v_add_f32_e32 v245, v97, v245
	v_cvt_pk_bf16_f32 v166, v92, v93
	v_cvt_pk_bf16_f32 v167, v94, v95
	ds_read_b64_tr_b16 v[92:93], v243 offset:26624
	ds_read_b64_tr_b16 v[94:95], v243 offset:27136
	v_mfma_f32_32x32x16_bf16 v[112:127], v[192:195], v[152:155], v[112:127]
	v_add_f32_e32 v245, v98, v245
	v_add_f32_e32 v245, v99, v245
	v_add_f32_e32 v245, v100, v245
	v_add_f32_e32 v245, v101, v245
	v_cvt_pk_bf16_f32 v168, v96, v97
	v_cvt_pk_bf16_f32 v169, v98, v99
	ds_read_b64_tr_b16 v[96:97], v243 offset:30720
	ds_read_b64_tr_b16 v[98:99], v243 offset:31232
	v_mfma_f32_32x32x16_bf16 v[128:143], v[196:199], v[152:155], v[128:143]
	v_add_f32_e32 v245, v102, v245
	v_add_f32_e32 v245, v103, v245
	v_add_f32_e32 v245, v104, v245
	v_add_f32_e32 v245, v105, v245
	v_cvt_pk_bf16_f32 v170, v100, v101
	v_cvt_pk_bf16_f32 v171, v102, v103
	ds_read_b64_tr_b16 v[100:101], v243 offset:27648
	ds_read_b64_tr_b16 v[102:103], v243 offset:28160
	v_mfma_f32_32x32x16_bf16 v[112:127], v[200:203], v[156:159], v[112:127]
	v_add_f32_e32 v245, v106, v245
	v_add_f32_e32 v245, v107, v245
	v_add_f32_e32 v245, v108, v245
	v_add_f32_e32 v245, v109, v245
	v_cvt_pk_bf16_f32 v172, v104, v105
	v_cvt_pk_bf16_f32 v173, v106, v107
	ds_read_b64_tr_b16 v[104:105], v243 offset:31744
	ds_read_b64_tr_b16 v[106:107], v243 offset:32256
	v_mfma_f32_32x32x16_bf16 v[128:143], v[206:209], v[156:159], v[128:143]
	v_add_f32_e32 v245, v110, v245
	v_add_f32_e32 v245, v111, v245
	v_cvt_pk_bf16_f32 v174, v108, v109
	v_cvt_pk_bf16_f32 v175, v110, v111
	v_add_f32_e32 v211, v211, v245
	v_add_u32_e32 v244, s18, v219
	s_waitcnt lgkmcnt(8)
	v_mfma_f32_32x32x16_bf16 v[0:15], v[214:217], v[160:163], v[0:15]
	v_max3_f32 v246, v112, v113, v114
	v_max3_f32 v247, v115, v116, v117
	ds_read_b64_tr_b16 v[214:215], v243 offset:49152
	ds_read_b64_tr_b16 v[216:217], v243 offset:49664
	v_mfma_f32_32x32x16_bf16 v[16:31], v[80:83], v[160:163], v[16:31]
	s_add_i32 m0, s17, s54
	v_max3_f32 v246, v246, v118, v119
	v_max3_f32 v247, v247, v120, v121
	v_max3_f32 v246, v246, v122, v123
	v_max3_f32 v247, v247, v124, v125
	ds_read_b64_tr_b16 v[80:81], v243 offset:53248
	ds_read_b64_tr_b16 v[82:83], v243 offset:53760
	global_load_lds_dwordx4 v222, s[0:1]
	s_add_u32 s0, s0, 0x20000
	s_addc_u32 s1, s1, 0
	v_mfma_f32_32x32x16_bf16 v[0:15], v[84:87], v[164:167], v[0:15]
	s_add_i32 s21, s18, s54
	s_add_i32 m0, s21, 0x6000
	v_max3_f32 v246, v246, v126, v127
	v_max3_f32 v247, v247, v128, v129
	v_max3_f32 v246, v246, v130, v131
	v_max3_f32 v247, v247, v132, v133
	ds_read_b64_tr_b16 v[84:85], v243 offset:50176
	ds_read_b64_tr_b16 v[86:87], v243 offset:50688
	global_load_lds_dwordx4 v223, s[4:5]
	v_mfma_f32_32x32x16_bf16 v[16:31], v[88:91], v[164:167], v[16:31]
	s_add_i32 m0, s21, 0xc000
	v_max3_f32 v246, v246, v134, v135
	v_max3_f32 v247, v247, v136, v137
	v_max3_f32 v246, v246, v138, v139
	v_max3_f32 v247, v247, v140, v141
	ds_read_b64_tr_b16 v[88:89], v243 offset:54272
	ds_read_b64_tr_b16 v[90:91], v243 offset:54784
	global_load_lds_dwordx4 v224, s[4:5]
	s_add_u32 s4, s4, 0x20000
	s_addc_u32 s5, s5, 0
	s_waitcnt lgkmcnt(8)
	v_mfma_f32_32x32x16_bf16 v[0:15], v[92:95], v[168:171], v[0:15]
	v_max3_f32 v246, v246, v142, v143
	v_max_f32_e32 v248, v246, v247
	v_mov_b32_e32 v246, v248
	ds_read_b64_tr_b16 v[92:93], v243 offset:51200
	ds_read_b64_tr_b16 v[94:95], v243 offset:51712
	v_permlane32_swap_b32_e32 v248, v246
	v_max_f32_e32 v248, v248, v246
	v_cmp_lt_f32_e32 vcc, s87, v248
	s_cbranch_vccnz .Lat_rare_M1
; #define WAIT_BAR(N) asm volatile("s_waitcnt vmcnt(" #N ") lgkmcnt(0)\n\ts_barrier":::"memory")
;   #define RESC() do{ if(resc){ asm volatile("s_waitcnt lgkmcnt(0)":::"memory"); \
;       _Pragma("unroll") for(int d_=0;d_<2;++d_) _Pragma("unroll") for(int r=0;r<16;++r)o[d_][r]*=wsf[crow(r,hi)]; } }while(0)
;   #define ROT() do{sl_prev=sl_cur;sl_cur=sl_next;sl_next=(sl_next==(NSLOT-1)*SLOTB)?0:sl_next+SLOTB;}while(0)
; template<int THRL> __device__ __forceinline__ void attn_unit(int b,int qc,int vc,int qb,const bf16*Q,const bf16*__restrict__ K,const bf16*__restrict__ V,bf16*O,char*shm,const int tid){
;     ...
;   int t=1;
;     ...
;   for(;t+5<NT;t+=2){
;     STEP(pB0,pB1,pA0,pA1,t,true,true,true);     WAIT_BAR(2); RESC(); ROT();
;     STEP(pA0,pA1,pB0,pB1,t+1,true,true,true);   WAIT_BAR(2); RESC(); ROT();
.Lat_cont_M1:
	v_mfma_f32_32x32x16_bf16 v[16:31], v[96:99], v[168:171], v[16:31]
	v_exp_f32_e32 v112, v112
	v_exp_f32_e32 v113, v113
	v_exp_f32_e32 v114, v114
	ds_read_b64_tr_b16 v[96:97], v243 offset:55296
	ds_read_b64_tr_b16 v[98:99], v243 offset:55808
	v_mfma_f32_32x32x16_bf16 v[0:15], v[100:103], v[172:175], v[0:15]
	v_exp_f32_e32 v115, v115
	v_exp_f32_e32 v116, v116
	v_exp_f32_e32 v117, v117
	ds_read_b64_tr_b16 v[100:101], v243 offset:52224
	ds_read_b64_tr_b16 v[102:103], v243 offset:52736
	v_mfma_f32_32x32x16_bf16 v[16:31], v[104:107], v[172:175], v[16:31]
	v_exp_f32_e32 v118, v118
	v_exp_f32_e32 v119, v119
	v_exp_f32_e32 v120, v120
	ds_read_b64_tr_b16 v[104:105], v243 offset:56320
	ds_read_b64_tr_b16 v[106:107], v243 offset:56832
	s_waitcnt lgkmcnt(8)
	v_mfma_f32_32x32x16_bf16 v[32:47], v[214:217], v[160:163], v[32:47]
	v_exp_f32_e32 v121, v121
	v_exp_f32_e32 v122, v122
	v_exp_f32_e32 v123, v123
	ds_read_b128 v[176:179], v244 offset:0
	ds_read_b128 v[180:183], v244 offset:512
	v_mfma_f32_32x32x16_bf16 v[48:63], v[80:83], v[160:163], v[48:63]
	v_exp_f32_e32 v124, v124
	v_exp_f32_e32 v125, v125
	v_exp_f32_e32 v126, v126
	ds_read_b128 v[184:187], v244 offset:2048
	ds_read_b128 v[188:191], v244 offset:2560
	v_mfma_f32_32x32x16_bf16 v[32:47], v[84:87], v[164:167], v[32:47]
	v_exp_f32_e32 v127, v127
	v_exp_f32_e32 v128, v128
	v_exp_f32_e32 v129, v129
	ds_read_b128 v[192:195], v244 offset:4096
	ds_read_b128 v[196:199], v244 offset:4608
	v_mfma_f32_32x32x16_bf16 v[48:63], v[88:91], v[164:167], v[48:63]
	v_exp_f32_e32 v130, v130
	v_exp_f32_e32 v131, v131
	v_exp_f32_e32 v132, v132
	ds_read_b128 v[200:203], v244 offset:6144
	ds_read_b128 v[206:209], v244 offset:6656
	s_waitcnt lgkmcnt(8)
	v_mfma_f32_32x32x16_bf16 v[32:47], v[92:95], v[168:171], v[32:47]
	v_exp_f32_e32 v133, v133
	v_exp_f32_e32 v134, v134
	v_exp_f32_e32 v135, v135
	v_mfma_f32_32x32x16_bf16 v[48:63], v[96:99], v[168:171], v[48:63]
	v_exp_f32_e32 v136, v136
	v_exp_f32_e32 v137, v137
	v_exp_f32_e32 v138, v138
	v_mfma_f32_32x32x16_bf16 v[32:47], v[100:103], v[172:175], v[32:47]
	v_exp_f32_e32 v139, v139
	v_exp_f32_e32 v140, v140
	v_exp_f32_e32 v141, v141
	v_mfma_f32_32x32x16_bf16 v[48:63], v[104:107], v[172:175], v[48:63]
	v_exp_f32_e32 v142, v142
	v_exp_f32_e32 v143, v143
	s_waitcnt vmcnt(3) lgkmcnt(0)
	s_barrier
	s_cbranch_vccz .Lat_noresc_M1
	v_mul_f32_e32 v0, v0, v250
	v_mul_f32_e32 v1, v1, v250
	v_mul_f32_e32 v2, v2, v250
	v_mul_f32_e32 v3, v3, v250
	v_mul_f32_e32 v4, v4, v250
	v_mul_f32_e32 v5, v5, v250
	v_mul_f32_e32 v6, v6, v250
	v_mul_f32_e32 v7, v7, v250
	v_mul_f32_e32 v8, v8, v250
	v_mul_f32_e32 v9, v9, v250
	v_mul_f32_e32 v10, v10, v250
	v_mul_f32_e32 v11, v11, v250
	v_mul_f32_e32 v12, v12, v250
	v_mul_f32_e32 v13, v13, v250
	v_mul_f32_e32 v14, v14, v250
	v_mul_f32_e32 v15, v15, v250
	v_mul_f32_e32 v16, v16, v250
	v_mul_f32_e32 v17, v17, v250
	v_mul_f32_e32 v18, v18, v250
	v_mul_f32_e32 v19, v19, v250
	v_mul_f32_e32 v20, v20, v250
	v_mul_f32_e32 v21, v21, v250
	v_mul_f32_e32 v22, v22, v250
	v_mul_f32_e32 v23, v23, v250
	v_mul_f32_e32 v24, v24, v250
	v_mul_f32_e32 v25, v25, v250
	v_mul_f32_e32 v26, v26, v250
	v_mul_f32_e32 v27, v27, v250
	v_mul_f32_e32 v28, v28, v250
	v_mul_f32_e32 v29, v29, v250
	v_mul_f32_e32 v30, v30, v250
	v_mul_f32_e32 v31, v31, v250
	v_mul_f32_e32 v32, v32, v250
	v_mul_f32_e32 v33, v33, v250
	v_mul_f32_e32 v34, v34, v250
	v_mul_f32_e32 v35, v35, v250
	v_mul_f32_e32 v36, v36, v250
	v_mul_f32_e32 v37, v37, v250
	v_mul_f32_e32 v38, v38, v250
	v_mul_f32_e32 v39, v39, v250
	v_mul_f32_e32 v40, v40, v250
	v_mul_f32_e32 v41, v41, v250
	v_mul_f32_e32 v42, v42, v250
	v_mul_f32_e32 v43, v43, v250
	v_mul_f32_e32 v44, v44, v250
	v_mul_f32_e32 v45, v45, v250
	v_mul_f32_e32 v46, v46, v250
	v_mul_f32_e32 v47, v47, v250
	v_mul_f32_e32 v48, v48, v250
	v_mul_f32_e32 v49, v49, v250
	v_mul_f32_e32 v50, v50, v250
	v_mul_f32_e32 v51, v51, v250
	v_mul_f32_e32 v52, v52, v250
	v_mul_f32_e32 v53, v53, v250
	v_mul_f32_e32 v54, v54, v250
	v_mul_f32_e32 v55, v55, v250
	v_mul_f32_e32 v56, v56, v250
	v_mul_f32_e32 v57, v57, v250
	v_mul_f32_e32 v58, v58, v250
	v_mul_f32_e32 v59, v59, v250
	v_mul_f32_e32 v60, v60, v250
	v_mul_f32_e32 v61, v61, v250
	v_mul_f32_e32 v62, v62, v250
	v_mul_f32_e32 v63, v63, v250

.Lat_step_M2:
	v_add_u32_e32 v243, s16, v204
	ds_read_b64_tr_b16 v[214:215], v243 offset:24576
	ds_read_b64_tr_b16 v[216:217], v243 offset:25088
	v_mfma_f32_32x32x16_bf16 v[80:95], v[176:179], v[144:147], v[64:79]
	v_add_f32_e32 v245, v112, v113
	v_add_f32_e32 v245, v114, v245
	v_add_f32_e32 v245, v115, v245
	v_add_f32_e32 v245, v116, v245
	v_add_f32_e32 v245, v117, v245
	v_cvt_pk_bf16_f32 v160, v112, v113
	v_cvt_pk_bf16_f32 v161, v114, v115
	ds_read_b64_tr_b16 v[112:113], v243 offset:28672
	ds_read_b64_tr_b16 v[114:115], v243 offset:29184
	v_mfma_f32_32x32x16_bf16 v[96:111], v[180:183], v[144:147], v[64:79]
	v_add_f32_e32 v245, v118, v245
	v_add_f32_e32 v245, v119, v245
	v_add_f32_e32 v245, v120, v245
	v_add_f32_e32 v245, v121, v245
	v_cvt_pk_bf16_f32 v162, v116, v117
	v_cvt_pk_bf16_f32 v163, v118, v119
	ds_read_b64_tr_b16 v[116:117], v243 offset:25600
	ds_read_b64_tr_b16 v[118:119], v243 offset:26112
	v_mfma_f32_32x32x16_bf16 v[80:95], v[184:187], v[148:151], v[80:95]
	v_add_f32_e32 v245, v122, v245
	v_add_f32_e32 v245, v123, v245
	v_add_f32_e32 v245, v124, v245
	v_add_f32_e32 v245, v125, v245
	v_cvt_pk_bf16_f32 v164, v120, v121
	v_cvt_pk_bf16_f32 v165, v122, v123
	ds_read_b64_tr_b16 v[120:121], v243 offset:29696
	ds_read_b64_tr_b16 v[122:123], v243 offset:30208
	v_mfma_f32_32x32x16_bf16 v[96:111], v[188:191], v[148:151], v[96:111]
	v_add_f32_e32 v245, v126, v245
	v_add_f32_e32 v245, v127, v245
	v_add_f32_e32 v245, v128, v245
	v_add_f32_e32 v245, v129, v245
	v_cvt_pk_bf16_f32 v166, v124, v125
	v_cvt_pk_bf16_f32 v167, v126, v127
	ds_read_b64_tr_b16 v[124:125], v243 offset:26624
	ds_read_b64_tr_b16 v[126:127], v243 offset:27136
	v_mfma_f32_32x32x16_bf16 v[80:95], v[192:195], v[152:155], v[80:95]
	v_add_f32_e32 v245, v130, v245
	v_add_f32_e32 v245, v131, v245
	v_add_f32_e32 v245, v132, v245
	v_add_f32_e32 v245, v133, v245
	v_cvt_pk_bf16_f32 v168, v128, v129
	v_cvt_pk_bf16_f32 v169, v130, v131
	ds_read_b64_tr_b16 v[128:129], v243 offset:30720
	ds_read_b64_tr_b16 v[130:131], v243 offset:31232
	v_mfma_f32_32x32x16_bf16 v[96:111], v[196:199], v[152:155], v[96:111]
	v_add_f32_e32 v245, v134, v245
	v_add_f32_e32 v245, v135, v245
	v_add_f32_e32 v245, v136, v245
	v_add_f32_e32 v245, v137, v245
	v_cvt_pk_bf16_f32 v170, v132, v133
	v_cvt_pk_bf16_f32 v171, v134, v135
	ds_read_b64_tr_b16 v[132:133], v243 offset:27648
	ds_read_b64_tr_b16 v[134:135], v243 offset:28160
	v_mfma_f32_32x32x16_bf16 v[80:95], v[200:203], v[156:159], v[80:95]
	v_add_f32_e32 v245, v138, v245
	v_add_f32_e32 v245, v139, v245
	v_add_f32_e32 v245, v140, v245
	v_add_f32_e32 v245, v141, v245
	v_cvt_pk_bf16_f32 v172, v136, v137
	v_cvt_pk_bf16_f32 v173, v138, v139
	ds_read_b64_tr_b16 v[136:137], v243 offset:31744
	ds_read_b64_tr_b16 v[138:139], v243 offset:32256
	v_mfma_f32_32x32x16_bf16 v[96:111], v[206:209], v[156:159], v[96:111]
	v_add_f32_e32 v245, v142, v245
	v_add_f32_e32 v245, v143, v245
	v_cvt_pk_bf16_f32 v174, v140, v141
	v_cvt_pk_bf16_f32 v175, v142, v143
	v_add_f32_e32 v211, v211, v245
	v_add_u32_e32 v244, s18, v219
	s_waitcnt lgkmcnt(8)
	v_mfma_f32_32x32x16_bf16 v[0:15], v[214:217], v[160:163], v[0:15]
	v_max3_f32 v246, v80, v81, v82
	v_max3_f32 v247, v83, v84, v85
	ds_read_b64_tr_b16 v[214:215], v243 offset:49152
	ds_read_b64_tr_b16 v[216:217], v243 offset:49664
	v_mfma_f32_32x32x16_bf16 v[16:31], v[112:115], v[160:163], v[16:31]
	s_add_i32 m0, s17, s54
	v_max3_f32 v246, v246, v86, v87
	v_max3_f32 v247, v247, v88, v89
	v_max3_f32 v246, v246, v90, v91
	v_max3_f32 v247, v247, v92, v93
	ds_read_b64_tr_b16 v[112:113], v243 offset:53248
	ds_read_b64_tr_b16 v[114:115], v243 offset:53760
	global_load_lds_dwordx4 v222, s[0:1]
	s_add_u32 s0, s0, 0x20000
	s_addc_u32 s1, s1, 0
	v_mfma_f32_32x32x16_bf16 v[0:15], v[116:119], v[164:167], v[0:15]
	s_add_i32 s21, s18, s54
	s_add_i32 m0, s21, 0x6000
	v_max3_f32 v246, v246, v94, v95
	v_max3_f32 v247, v247, v96, v97
	v_max3_f32 v246, v246, v98, v99
	v_max3_f32 v247, v247, v100, v101
	ds_read_b64_tr_b16 v[116:117], v243 offset:50176
	ds_read_b64_tr_b16 v[118:119], v243 offset:50688
	global_load_lds_dwordx4 v223, s[4:5]
	v_mfma_f32_32x32x16_bf16 v[16:31], v[120:123], v[164:167], v[16:31]
	s_add_i32 m0, s21, 0xc000
	v_max3_f32 v246, v246, v102, v103
	v_max3_f32 v247, v247, v104, v105
	v_max3_f32 v246, v246, v106, v107
	v_max3_f32 v247, v247, v108, v109
	ds_read_b64_tr_b16 v[120:121], v243 offset:54272
	ds_read_b64_tr_b16 v[122:123], v243 offset:54784
	global_load_lds_dwordx4 v224, s[4:5]
	s_add_u32 s4, s4, 0x20000
	s_addc_u32 s5, s5, 0
	s_waitcnt lgkmcnt(8)
	v_mfma_f32_32x32x16_bf16 v[0:15], v[124:127], v[168:171], v[0:15]
	v_max3_f32 v246, v246, v110, v111
	v_max_f32_e32 v248, v246, v247
	v_mov_b32_e32 v246, v248
	ds_read_b64_tr_b16 v[124:125], v243 offset:51200
	ds_read_b64_tr_b16 v[126:127], v243 offset:51712
	v_permlane32_swap_b32_e32 v248, v246
	v_max_f32_e32 v248, v248, v246
	v_cmp_lt_f32_e32 vcc, s87, v248
	s_cbranch_vccnz .Lat_rare_M2
; #define WAIT_BAR(N) asm volatile("s_waitcnt vmcnt(" #N ") lgkmcnt(0)\n\ts_barrier":::"memory")
;   #define RESC() do{ if(resc){ asm volatile("s_waitcnt lgkmcnt(0)":::"memory"); \
;       _Pragma("unroll") for(int d_=0;d_<2;++d_) _Pragma("unroll") for(int r=0;r<16;++r)o[d_][r]*=wsf[crow(r,hi)]; } }while(0)
;   #define ROT() do{sl_prev=sl_cur;sl_cur=sl_next;sl_next=(sl_next==(NSLOT-1)*SLOTB)?0:sl_next+SLOTB;}while(0)
; template<int THRL> __device__ __forceinline__ void attn_unit(int b,int qc,int vc,int qb,const bf16*Q,const bf16*__restrict__ K,const bf16*__restrict__ V,bf16*O,char*shm,const int tid){
;     ...
;   int t=1;
;     ...
;   for(;t+5<NT;t+=2){
;     STEP(pB0,pB1,pA0,pA1,t,true,true,true);     WAIT_BAR(2); RESC(); ROT();
;     STEP(pA0,pA1,pB0,pB1,t+1,true,true,true);   WAIT_BAR(2); RESC(); ROT();
.Lat_cont_M2:
	v_mfma_f32_32x32x16_bf16 v[16:31], v[128:131], v[168:171], v[16:31]
	v_exp_f32_e32 v80, v80
	v_exp_f32_e32 v81, v81
	v_exp_f32_e32 v82, v82
	ds_read_b64_tr_b16 v[128:129], v243 offset:55296
	ds_read_b64_tr_b16 v[130:131], v243 offset:55808
	v_mfma_f32_32x32x16_bf16 v[0:15], v[132:135], v[172:175], v[0:15]
	v_exp_f32_e32 v83, v83
	v_exp_f32_e32 v84, v84
	v_exp_f32_e32 v85, v85
	ds_read_b64_tr_b16 v[132:133], v243 offset:52224
	ds_read_b64_tr_b16 v[134:135], v243 offset:52736
	v_mfma_f32_32x32x16_bf16 v[16:31], v[136:139], v[172:175], v[16:31]
	v_exp_f32_e32 v86, v86
	v_exp_f32_e32 v87, v87
	v_exp_f32_e32 v88, v88
	ds_read_b64_tr_b16 v[136:137], v243 offset:56320
	ds_read_b64_tr_b16 v[138:139], v243 offset:56832
	s_waitcnt lgkmcnt(8)
	v_mfma_f32_32x32x16_bf16 v[32:47], v[214:217], v[160:163], v[32:47]
	v_exp_f32_e32 v89, v89
	v_exp_f32_e32 v90, v90
	v_exp_f32_e32 v91, v91
	ds_read_b128 v[176:179], v244 offset:0
	ds_read_b128 v[180:183], v244 offset:512
	v_mfma_f32_32x32x16_bf16 v[48:63], v[112:115], v[160:163], v[48:63]
	v_exp_f32_e32 v92, v92
	v_exp_f32_e32 v93, v93
	v_exp_f32_e32 v94, v94
	ds_read_b128 v[184:187], v244 offset:2048
	ds_read_b128 v[188:191], v244 offset:2560
	v_mfma_f32_32x32x16_bf16 v[32:47], v[116:119], v[164:167], v[32:47]
	v_exp_f32_e32 v95, v95
	v_exp_f32_e32 v96, v96
	v_exp_f32_e32 v97, v97
	ds_read_b128 v[192:195], v244 offset:4096
	ds_read_b128 v[196:199], v244 offset:4608
	v_mfma_f32_32x32x16_bf16 v[48:63], v[120:123], v[164:167], v[48:63]
	v_exp_f32_e32 v98, v98
	v_exp_f32_e32 v99, v99
	v_exp_f32_e32 v100, v100
	ds_read_b128 v[200:203], v244 offset:6144
	ds_read_b128 v[206:209], v244 offset:6656
	s_waitcnt lgkmcnt(8)
	v_mfma_f32_32x32x16_bf16 v[32:47], v[124:127], v[168:171], v[32:47]
	v_exp_f32_e32 v101, v101
	v_exp_f32_e32 v102, v102
	v_exp_f32_e32 v103, v103
	v_mfma_f32_32x32x16_bf16 v[48:63], v[128:131], v[168:171], v[48:63]
	v_exp_f32_e32 v104, v104
	v_exp_f32_e32 v105, v105
	v_exp_f32_e32 v106, v106
	v_mfma_f32_32x32x16_bf16 v[32:47], v[132:135], v[172:175], v[32:47]
	v_exp_f32_e32 v107, v107
	v_exp_f32_e32 v108, v108
	v_exp_f32_e32 v109, v109
	v_mfma_f32_32x32x16_bf16 v[48:63], v[136:139], v[172:175], v[48:63]
	v_exp_f32_e32 v110, v110
	v_exp_f32_e32 v111, v111
	s_waitcnt vmcnt(3) lgkmcnt(0)
	s_barrier
	s_cbranch_vccz .Lat_noresc_M2
	v_mul_f32_e32 v0, v0, v250
	v_mul_f32_e32 v1, v1, v250
	v_mul_f32_e32 v2, v2, v250
	v_mul_f32_e32 v3, v3, v250
	v_mul_f32_e32 v4, v4, v250
	v_mul_f32_e32 v5, v5, v250
	v_mul_f32_e32 v6, v6, v250
	v_mul_f32_e32 v7, v7, v250
	v_mul_f32_e32 v8, v8, v250
	v_mul_f32_e32 v9, v9, v250
	v_mul_f32_e32 v10, v10, v250
	v_mul_f32_e32 v11, v11, v250
	v_mul_f32_e32 v12, v12, v250
	v_mul_f32_e32 v13, v13, v250
	v_mul_f32_e32 v14, v14, v250
	v_mul_f32_e32 v15, v15, v250
	v_mul_f32_e32 v16, v16, v250
	v_mul_f32_e32 v17, v17, v250
	v_mul_f32_e32 v18, v18, v250
	v_mul_f32_e32 v19, v19, v250
	v_mul_f32_e32 v20, v20, v250
	v_mul_f32_e32 v21, v21, v250
	v_mul_f32_e32 v22, v22, v250
	v_mul_f32_e32 v23, v23, v250
	v_mul_f32_e32 v24, v24, v250
	v_mul_f32_e32 v25, v25, v250
	v_mul_f32_e32 v26, v26, v250
	v_mul_f32_e32 v27, v27, v250
	v_mul_f32_e32 v28, v28, v250
	v_mul_f32_e32 v29, v29, v250
	v_mul_f32_e32 v30, v30, v250
	v_mul_f32_e32 v31, v31, v250
	v_mul_f32_e32 v32, v32, v250
	v_mul_f32_e32 v33, v33, v250
	v_mul_f32_e32 v34, v34, v250
	v_mul_f32_e32 v35, v35, v250
	v_mul_f32_e32 v36, v36, v250
	v_mul_f32_e32 v37, v37, v250
	v_mul_f32_e32 v38, v38, v250
	v_mul_f32_e32 v39, v39, v250
	v_mul_f32_e32 v40, v40, v250
	v_mul_f32_e32 v41, v41, v250
	v_mul_f32_e32 v42, v42, v250
	v_mul_f32_e32 v43, v43, v250
	v_mul_f32_e32 v44, v44, v250
	v_mul_f32_e32 v45, v45, v250
	v_mul_f32_e32 v46, v46, v250
	v_mul_f32_e32 v47, v47, v250
	v_mul_f32_e32 v48, v48, v250
	v_mul_f32_e32 v49, v49, v250
	v_mul_f32_e32 v50, v50, v250
	v_mul_f32_e32 v51, v51, v250
	v_mul_f32_e32 v52, v52, v250
	v_mul_f32_e32 v53, v53, v250
	v_mul_f32_e32 v54, v54, v250
	v_mul_f32_e32 v55, v55, v250
	v_mul_f32_e32 v56, v56, v250
	v_mul_f32_e32 v57, v57, v250
	v_mul_f32_e32 v58, v58, v250
	v_mul_f32_e32 v59, v59, v250
	v_mul_f32_e32 v60, v60, v250
	v_mul_f32_e32 v61, v61, v250
	v_mul_f32_e32 v62, v62, v250
	v_mul_f32_e32 v63, v63, v250

.Lat_step_T5:
	v_add_u32_e32 v243, s16, v204
	ds_read_b64_tr_b16 v[214:215], v243 offset:24576
	ds_read_b64_tr_b16 v[216:217], v243 offset:25088
	v_mfma_f32_32x32x16_bf16 v[112:127], v[176:179], v[144:147], v[64:79]
	v_add_f32_e32 v245, v80, v81
	v_add_f32_e32 v245, v82, v245
	v_add_f32_e32 v245, v83, v245
	v_add_f32_e32 v245, v84, v245
	v_add_f32_e32 v245, v85, v245
	v_cvt_pk_bf16_f32 v160, v80, v81
	v_cvt_pk_bf16_f32 v161, v82, v83
	ds_read_b64_tr_b16 v[80:81], v243 offset:28672
	ds_read_b64_tr_b16 v[82:83], v243 offset:29184
	v_mfma_f32_32x32x16_bf16 v[128:143], v[180:183], v[144:147], v[64:79]
	v_add_f32_e32 v245, v86, v245
	v_add_f32_e32 v245, v87, v245
	v_add_f32_e32 v245, v88, v245
	v_add_f32_e32 v245, v89, v245
	v_cvt_pk_bf16_f32 v162, v84, v85
	v_cvt_pk_bf16_f32 v163, v86, v87
	ds_read_b64_tr_b16 v[84:85], v243 offset:25600
	ds_read_b64_tr_b16 v[86:87], v243 offset:26112
	v_mfma_f32_32x32x16_bf16 v[112:127], v[184:187], v[148:151], v[112:127]
	v_add_f32_e32 v245, v90, v245
	v_add_f32_e32 v245, v91, v245
	v_add_f32_e32 v245, v92, v245
	v_add_f32_e32 v245, v93, v245
	v_cvt_pk_bf16_f32 v164, v88, v89
	v_cvt_pk_bf16_f32 v165, v90, v91
	ds_read_b64_tr_b16 v[88:89], v243 offset:29696
	ds_read_b64_tr_b16 v[90:91], v243 offset:30208
	v_mfma_f32_32x32x16_bf16 v[128:143], v[188:191], v[148:151], v[128:143]
	v_add_f32_e32 v245, v94, v245
	v_add_f32_e32 v245, v95, v245
	v_add_f32_e32 v245, v96, v245
	v_add_f32_e32 v245, v97, v245
	v_cvt_pk_bf16_f32 v166, v92, v93
	v_cvt_pk_bf16_f32 v167, v94, v95
	ds_read_b64_tr_b16 v[92:93], v243 offset:26624
	ds_read_b64_tr_b16 v[94:95], v243 offset:27136
	v_mfma_f32_32x32x16_bf16 v[112:127], v[192:195], v[152:155], v[112:127]
	v_add_f32_e32 v245, v98, v245
	v_add_f32_e32 v245, v99, v245
	v_add_f32_e32 v245, v100, v245
	v_add_f32_e32 v245, v101, v245
	v_cvt_pk_bf16_f32 v168, v96, v97
	v_cvt_pk_bf16_f32 v169, v98, v99
	ds_read_b64_tr_b16 v[96:97], v243 offset:30720
	ds_read_b64_tr_b16 v[98:99], v243 offset:31232
	v_mfma_f32_32x32x16_bf16 v[128:143], v[196:199], v[152:155], v[128:143]
	v_add_f32_e32 v245, v102, v245
	v_add_f32_e32 v245, v103, v245
	v_add_f32_e32 v245, v104, v245
	v_add_f32_e32 v245, v105, v245
	v_cvt_pk_bf16_f32 v170, v100, v101
	v_cvt_pk_bf16_f32 v171, v102, v103
	ds_read_b64_tr_b16 v[100:101], v243 offset:27648
	ds_read_b64_tr_b16 v[102:103], v243 offset:28160
	v_mfma_f32_32x32x16_bf16 v[112:127], v[200:203], v[156:159], v[112:127]
	v_add_f32_e32 v245, v106, v245
	v_add_f32_e32 v245, v107, v245
	v_add_f32_e32 v245, v108, v245
	v_add_f32_e32 v245, v109, v245
	v_cvt_pk_bf16_f32 v172, v104, v105
	v_cvt_pk_bf16_f32 v173, v106, v107
	ds_read_b64_tr_b16 v[104:105], v243 offset:31744
	ds_read_b64_tr_b16 v[106:107], v243 offset:32256
	v_mfma_f32_32x32x16_bf16 v[128:143], v[206:209], v[156:159], v[128:143]
	v_add_f32_e32 v245, v110, v245
	v_add_f32_e32 v245, v111, v245
	v_cvt_pk_bf16_f32 v174, v108, v109
	v_cvt_pk_bf16_f32 v175, v110, v111
	v_add_f32_e32 v211, v211, v245
	v_add_u32_e32 v244, s18, v219
	s_waitcnt lgkmcnt(8)
	v_mfma_f32_32x32x16_bf16 v[0:15], v[214:217], v[160:163], v[0:15]
	v_max3_f32 v246, v112, v113, v114
	v_max3_f32 v247, v115, v116, v117
	ds_read_b64_tr_b16 v[214:215], v243 offset:49152
	ds_read_b64_tr_b16 v[216:217], v243 offset:49664
	v_mfma_f32_32x32x16_bf16 v[16:31], v[80:83], v[160:163], v[16:31]
	s_add_i32 m0, s17, s54
	v_max3_f32 v246, v246, v118, v119
	v_max3_f32 v247, v247, v120, v121
	v_max3_f32 v246, v246, v122, v123
	v_max3_f32 v247, v247, v124, v125
	ds_read_b64_tr_b16 v[80:81], v243 offset:53248
	ds_read_b64_tr_b16 v[82:83], v243 offset:53760
	global_load_lds_dwordx4 v222, s[0:1]
	s_add_u32 s0, s0, 0x20000
	s_addc_u32 s1, s1, 0
	v_mfma_f32_32x32x16_bf16 v[0:15], v[84:87], v[164:167], v[0:15]
	s_add_i32 s21, s18, s54
	s_add_i32 m0, s21, 0x6000
	v_max3_f32 v246, v246, v126, v127
	v_max3_f32 v247, v247, v128, v129
	v_max3_f32 v246, v246, v130, v131
	v_max3_f32 v247, v247, v132, v133
	ds_read_b64_tr_b16 v[84:85], v243 offset:50176
	ds_read_b64_tr_b16 v[86:87], v243 offset:50688
	global_load_lds_dwordx4 v223, s[4:5]
	v_mfma_f32_32x32x16_bf16 v[16:31], v[88:91], v[164:167], v[16:31]
	s_add_i32 m0, s21, 0xc000
	v_max3_f32 v246, v246, v134, v135
	v_max3_f32 v247, v247, v136, v137
	v_max3_f32 v246, v246, v138, v139
	v_max3_f32 v247, v247, v140, v141
	ds_read_b64_tr_b16 v[88:89], v243 offset:54272
	ds_read_b64_tr_b16 v[90:91], v243 offset:54784
	global_load_lds_dwordx4 v224, s[4:5]
	s_add_u32 s4, s4, 0x20000
	s_addc_u32 s5, s5, 0
	s_waitcnt lgkmcnt(8)
	v_mfma_f32_32x32x16_bf16 v[0:15], v[92:95], v[168:171], v[0:15]
	v_max3_f32 v246, v246, v142, v143
	v_max_f32_e32 v248, v246, v247
	v_mov_b32_e32 v246, v248
	ds_read_b64_tr_b16 v[92:93], v243 offset:51200
	ds_read_b64_tr_b16 v[94:95], v243 offset:51712
	v_permlane32_swap_b32_e32 v248, v246
	v_max_f32_e32 v248, v248, v246
	v_cmp_lt_f32_e32 vcc, s87, v248
	s_cbranch_vccnz .Lat_rare_T5

; __device__ __forceinline__ void cmask(f32x16&p0,f32x16&p1,int jb,int qrel,int hi){
;   const float NEG=-INFINITY; int kb=64*jb+4*hi;
;   #pragma unroll
;   for(int r=0;r<16;++r){int kv=kb+(r&3)+8*(r>>2); if(kv>qrel)p0[r]=NEG; if(kv+32>qrel)p1[r]=NEG;}
; }
.Lat_step_T4:
	v_add_u32_e32 v243, s16, v204
	ds_read_b64_tr_b16 v[214:215], v243 offset:24576
	ds_read_b64_tr_b16 v[216:217], v243 offset:25088
	v_mfma_f32_32x32x16_bf16 v[80:95], v[176:179], v[144:147], v[64:79]
	v_add_f32_e32 v245, v112, v113
	v_add_f32_e32 v245, v114, v245
	v_add_f32_e32 v245, v115, v245
	v_add_f32_e32 v245, v116, v245
	v_add_f32_e32 v245, v117, v245
	v_cvt_pk_bf16_f32 v160, v112, v113
	v_cvt_pk_bf16_f32 v161, v114, v115
	ds_read_b64_tr_b16 v[112:113], v243 offset:28672
	ds_read_b64_tr_b16 v[114:115], v243 offset:29184
	v_mfma_f32_32x32x16_bf16 v[96:111], v[180:183], v[144:147], v[64:79]
	v_add_f32_e32 v245, v118, v245
	v_add_f32_e32 v245, v119, v245
	v_add_f32_e32 v245, v120, v245
	v_add_f32_e32 v245, v121, v245
	v_cvt_pk_bf16_f32 v162, v116, v117
	v_cvt_pk_bf16_f32 v163, v118, v119
	ds_read_b64_tr_b16 v[116:117], v243 offset:25600
	ds_read_b64_tr_b16 v[118:119], v243 offset:26112
	v_mfma_f32_32x32x16_bf16 v[80:95], v[184:187], v[148:151], v[80:95]
	v_add_f32_e32 v245, v122, v245
	v_add_f32_e32 v245, v123, v245
	v_add_f32_e32 v245, v124, v245
	v_add_f32_e32 v245, v125, v245
	v_cvt_pk_bf16_f32 v164, v120, v121
	v_cvt_pk_bf16_f32 v165, v122, v123
	ds_read_b64_tr_b16 v[120:121], v243 offset:29696
	ds_read_b64_tr_b16 v[122:123], v243 offset:30208
	v_mfma_f32_32x32x16_bf16 v[96:111], v[188:191], v[148:151], v[96:111]
	v_add_f32_e32 v245, v126, v245
	v_add_f32_e32 v245, v127, v245
	v_add_f32_e32 v245, v128, v245
	v_add_f32_e32 v245, v129, v245
	v_cvt_pk_bf16_f32 v166, v124, v125
	v_cvt_pk_bf16_f32 v167, v126, v127
	ds_read_b64_tr_b16 v[124:125], v243 offset:26624
	ds_read_b64_tr_b16 v[126:127], v243 offset:27136
	v_mfma_f32_32x32x16_bf16 v[80:95], v[192:195], v[152:155], v[80:95]
	v_add_f32_e32 v245, v130, v245
	v_add_f32_e32 v245, v131, v245
	v_add_f32_e32 v245, v132, v245
	v_add_f32_e32 v245, v133, v245
	v_cvt_pk_bf16_f32 v168, v128, v129
	v_cvt_pk_bf16_f32 v169, v130, v131
	ds_read_b64_tr_b16 v[128:129], v243 offset:30720
	ds_read_b64_tr_b16 v[130:131], v243 offset:31232
	v_mfma_f32_32x32x16_bf16 v[96:111], v[196:199], v[152:155], v[96:111]
	v_add_f32_e32 v245, v134, v245
	v_add_f32_e32 v245, v135, v245
	v_add_f32_e32 v245, v136, v245
	v_add_f32_e32 v245, v137, v245
	v_cvt_pk_bf16_f32 v170, v132, v133
	v_cvt_pk_bf16_f32 v171, v134, v135
	ds_read_b64_tr_b16 v[132:133], v243 offset:27648
	ds_read_b64_tr_b16 v[134:135], v243 offset:28160
	v_mfma_f32_32x32x16_bf16 v[80:95], v[200:203], v[156:159], v[80:95]
	v_add_f32_e32 v245, v138, v245
	v_add_f32_e32 v245, v139, v245
	v_add_f32_e32 v245, v140, v245
	v_add_f32_e32 v245, v141, v245
	v_cvt_pk_bf16_f32 v172, v136, v137
	v_cvt_pk_bf16_f32 v173, v138, v139
	ds_read_b64_tr_b16 v[136:137], v243 offset:31744
	ds_read_b64_tr_b16 v[138:139], v243 offset:32256
	v_mfma_f32_32x32x16_bf16 v[96:111], v[206:209], v[156:159], v[96:111]
	v_add_f32_e32 v245, v142, v245
	v_add_f32_e32 v245, v143, v245
	v_cvt_pk_bf16_f32 v174, v140, v141
	v_cvt_pk_bf16_f32 v175, v142, v143
	v_add_f32_e32 v211, v211, v245
	v_add_u32_e32 v244, s18, v219
	s_waitcnt lgkmcnt(8)
	v_mfma_f32_32x32x16_bf16 v[0:15], v[214:217], v[160:163], v[0:15]
	v_cmp_gt_i32_e64 s[28:29], 0, v225
	v_cmp_gt_i32_e64 s[30:31], 1, v225
	v_cmp_gt_i32_e64 s[34:35], 2, v225
	v_cndmask_b32_e64 v80, v80, v241, s[28:29]
	v_cmp_gt_i32_e64 s[28:29], 3, v225
	v_cndmask_b32_e64 v81, v81, v241, s[30:31]
	v_cmp_gt_i32_e64 s[30:31], 8, v225
	v_cndmask_b32_e64 v82, v82, v241, s[34:35]
	v_cmp_gt_i32_e64 s[34:35], 9, v225
	v_cndmask_b32_e64 v83, v83, v241, s[28:29]
	ds_read_b64_tr_b16 v[214:215], v243 offset:49152
	ds_read_b64_tr_b16 v[216:217], v243 offset:49664
	v_mfma_f32_32x32x16_bf16 v[16:31], v[112:115], v[160:163], v[16:31]
	s_add_i32 m0, s17, s54
	v_cmp_gt_i32_e64 s[28:29], 10, v225
	v_cndmask_b32_e64 v84, v84, v241, s[30:31]
	v_cmp_gt_i32_e64 s[30:31], 11, v225
	v_cndmask_b32_e64 v85, v85, v241, s[34:35]
	v_cmp_gt_i32_e64 s[34:35], 16, v225
	v_cndmask_b32_e64 v86, v86, v241, s[28:29]
	v_cmp_gt_i32_e64 s[28:29], 17, v225
	v_cndmask_b32_e64 v87, v87, v241, s[30:31]
	v_cmp_gt_i32_e64 s[30:31], 18, v225
	v_cndmask_b32_e64 v88, v88, v241, s[34:35]
	ds_read_b64_tr_b16 v[112:113], v243 offset:53248
	ds_read_b64_tr_b16 v[114:115], v243 offset:53760
	global_load_lds_dwordx4 v222, s[0:1]
	s_add_u32 s0, s0, 0x20000
	s_addc_u32 s1, s1, 0
	v_mfma_f32_32x32x16_bf16 v[0:15], v[116:119], v[164:167], v[0:15]
	s_add_i32 s21, s18, s54
	s_add_i32 m0, s21, 0x6000
	v_cmp_gt_i32_e64 s[34:35], 19, v225
	v_cndmask_b32_e64 v89, v89, v241, s[28:29]
	v_cmp_gt_i32_e64 s[28:29], 24, v225
	v_cndmask_b32_e64 v90, v90, v241, s[30:31]
	v_cmp_gt_i32_e64 s[30:31], 25, v225
	v_cndmask_b32_e64 v91, v91, v241, s[34:35]
	v_cmp_gt_i32_e64 s[34:35], 26, v225
	v_cndmask_b32_e64 v92, v92, v241, s[28:29]
	v_cmp_gt_i32_e64 s[28:29], 27, v225
	v_cndmask_b32_e64 v93, v93, v241, s[30:31]
	ds_read_b64_tr_b16 v[116:117], v243 offset:50176
	ds_read_b64_tr_b16 v[118:119], v243 offset:50688
	global_load_lds_dwordx4 v223, s[4:5]
	v_mfma_f32_32x32x16_bf16 v[16:31], v[120:123], v[164:167], v[16:31]
	s_add_i32 m0, s21, 0xc000
	v_cmp_gt_i32_e64 s[30:31], 32, v225
	v_cndmask_b32_e64 v94, v94, v241, s[34:35]
	v_cmp_gt_i32_e64 s[34:35], 33, v225
	v_cndmask_b32_e64 v95, v95, v241, s[28:29]
	v_cmp_gt_i32_e64 s[28:29], 34, v225
	v_cndmask_b32_e64 v96, v96, v241, s[30:31]
	v_cmp_gt_i32_e64 s[30:31], 35, v225
	v_cndmask_b32_e64 v97, v97, v241, s[34:35]
	v_cmp_gt_i32_e64 s[34:35], 40, v225
	v_cndmask_b32_e64 v98, v98, v241, s[28:29]
	ds_read_b64_tr_b16 v[120:121], v243 offset:54272
	ds_read_b64_tr_b16 v[122:123], v243 offset:54784
	global_load_lds_dwordx4 v224, s[4:5]
	s_add_u32 s4, s4, 0x20000
	s_addc_u32 s5, s5, 0
	s_waitcnt lgkmcnt(8)
	v_mfma_f32_32x32x16_bf16 v[0:15], v[124:127], v[168:171], v[0:15]
	v_cmp_gt_i32_e64 s[28:29], 41, v225
	v_cndmask_b32_e64 v99, v99, v241, s[30:31]
	v_cmp_gt_i32_e64 s[30:31], 42, v225
	v_cndmask_b32_e64 v100, v100, v241, s[34:35]
	v_cmp_gt_i32_e64 s[34:35], 43, v225
	v_cndmask_b32_e64 v101, v101, v241, s[28:29]
	v_cmp_gt_i32_e64 s[28:29], 48, v225
	v_cndmask_b32_e64 v102, v102, v241, s[30:31]
	v_cmp_gt_i32_e64 s[30:31], 49, v225
	v_cndmask_b32_e64 v103, v103, v241, s[34:35]
	ds_read_b64_tr_b16 v[124:125], v243 offset:51200
	ds_read_b64_tr_b16 v[126:127], v243 offset:51712
	v_mfma_f32_32x32x16_bf16 v[16:31], v[128:131], v[168:171], v[16:31]
	v_cmp_gt_i32_e64 s[34:35], 50, v225
	v_cndmask_b32_e64 v104, v104, v241, s[28:29]
	v_cmp_gt_i32_e64 s[28:29], 51, v225
	v_cndmask_b32_e64 v105, v105, v241, s[30:31]
	v_cmp_gt_i32_e64 s[30:31], 56, v225
	v_cndmask_b32_e64 v106, v106, v241, s[34:35]
	v_cmp_gt_i32_e64 s[34:35], 57, v225
	v_cndmask_b32_e64 v107, v107, v241, s[28:29]
	v_cmp_gt_i32_e64 s[28:29], 58, v225
	v_cndmask_b32_e64 v108, v108, v241, s[30:31]
	ds_read_b64_tr_b16 v[128:129], v243 offset:55296
	ds_read_b64_tr_b16 v[130:131], v243 offset:55808
	v_mfma_f32_32x32x16_bf16 v[0:15], v[132:135], v[172:175], v[0:15]
	v_cmp_gt_i32_e64 s[30:31], 59, v225
	v_cndmask_b32_e64 v109, v109, v241, s[34:35]
	v_cndmask_b32_e64 v110, v110, v241, s[28:29]
	v_cndmask_b32_e64 v111, v111, v241, s[30:31]
	v_max3_f32 v246, v80, v81, v82
	v_max3_f32 v247, v83, v84, v85
	v_max3_f32 v246, v246, v86, v87
	v_max3_f32 v247, v247, v88, v89
	v_max3_f32 v246, v246, v90, v91
	v_max3_f32 v247, v247, v92, v93
	ds_read_b64_tr_b16 v[132:133], v243 offset:52224
	ds_read_b64_tr_b16 v[134:135], v243 offset:52736
	v_mfma_f32_32x32x16_bf16 v[16:31], v[136:139], v[172:175], v[16:31]
	v_max3_f32 v246, v246, v94, v95
	v_max3_f32 v247, v247, v96, v97
	v_max3_f32 v246, v246, v98, v99
	v_max3_f32 v247, v247, v100, v101
	v_max3_f32 v246, v246, v102, v103
	v_max3_f32 v247, v247, v104, v105
	v_max3_f32 v246, v246, v106, v107
	v_max3_f32 v247, v247, v108, v109
	v_max3_f32 v246, v246, v110, v111
	v_max_f32_e32 v248, v246, v247
	ds_read_b64_tr_b16 v[136:137], v243 offset:56320
	ds_read_b64_tr_b16 v[138:139], v243 offset:56832
	s_waitcnt lgkmcnt(8)
	v_mfma_f32_32x32x16_bf16 v[32:47], v[214:217], v[160:163], v[32:47]
	v_mov_b32_e32 v246, v248
	s_nop 1
	v_permlane32_swap_b32_e32 v248, v246
	v_max_f32_e32 v248, v248, v246
	ds_read_b128 v[176:179], v244 offset:0
	ds_read_b128 v[180:183], v244 offset:512
	v_cmp_lt_f32_e32 vcc, s87, v248
	s_cbranch_vccnz .Lat_rare_T4
.Lat_cont_T4:
	v_mfma_f32_32x32x16_bf16 v[48:63], v[112:115], v[160:163], v[48:63]
	v_exp_f32_e32 v80, v80
	v_exp_f32_e32 v81, v81
	v_exp_f32_e32 v82, v82
	v_exp_f32_e32 v83, v83
	v_exp_f32_e32 v84, v84
	ds_read_b128 v[184:187], v244 offset:2048
	ds_read_b128 v[188:191], v244 offset:2560
	v_mfma_f32_32x32x16_bf16 v[32:47], v[116:119], v[164:167], v[32:47]
	v_exp_f32_e32 v85, v85
	v_exp_f32_e32 v86, v86
	v_exp_f32_e32 v87, v87
	v_exp_f32_e32 v88, v88
	v_exp_f32_e32 v89, v89
	ds_read_b128 v[192:195], v244 offset:4096
	ds_read_b128 v[196:199], v244 offset:4608
	v_mfma_f32_32x32x16_bf16 v[48:63], v[120:123], v[164:167], v[48:63]
	v_exp_f32_e32 v90, v90
	v_exp_f32_e32 v91, v91
	v_exp_f32_e32 v92, v92
	v_exp_f32_e32 v93, v93
	v_exp_f32_e32 v94, v94
	ds_read_b128 v[200:203], v244 offset:6144
	ds_read_b128 v[206:209], v244 offset:6656
	s_waitcnt lgkmcnt(8)
	v_mfma_f32_32x32x16_bf16 v[32:47], v[124:127], v[168:171], v[32:47]
	v_exp_f32_e32 v95, v95
	v_exp_f32_e32 v96, v96
	v_exp_f32_e32 v97, v97
	v_exp_f32_e32 v98, v98
	v_exp_f32_e32 v99, v99
	v_mfma_f32_32x32x16_bf16 v[48:63], v[128:131], v[168:171], v[48:63]
	v_exp_f32_e32 v100, v100
	v_exp_f32_e32 v101, v101
	v_exp_f32_e32 v102, v102
	v_exp_f32_e32 v103, v103
	v_mfma_f32_32x32x16_bf16 v[32:47], v[132:135], v[172:175], v[32:47]
	v_exp_f32_e32 v104, v104
	v_exp_f32_e32 v105, v105
	v_exp_f32_e32 v106, v106
	v_exp_f32_e32 v107, v107
	v_mfma_f32_32x32x16_bf16 v[48:63], v[136:139], v[172:175], v[48:63]
	v_exp_f32_e32 v108, v108
	v_exp_f32_e32 v109, v109
	v_exp_f32_e32 v110, v110
	v_exp_f32_e32 v111, v111
	s_waitcnt vmcnt(3) lgkmcnt(0)
	s_barrier
	s_cbranch_vccz .Lat_noresc_T4
	v_mul_f32_e32 v0, v0, v250
	v_mul_f32_e32 v1, v1, v250
	v_mul_f32_e32 v2, v2, v250
	v_mul_f32_e32 v3, v3, v250
	v_mul_f32_e32 v4, v4, v250
	v_mul_f32_e32 v5, v5, v250
	v_mul_f32_e32 v6, v6, v250
	v_mul_f32_e32 v7, v7, v250
	v_mul_f32_e32 v8, v8, v250
	v_mul_f32_e32 v9, v9, v250
	v_mul_f32_e32 v10, v10, v250
	v_mul_f32_e32 v11, v11, v250
	v_mul_f32_e32 v12, v12, v250
	v_mul_f32_e32 v13, v13, v250
	v_mul_f32_e32 v14, v14, v250
	v_mul_f32_e32 v15, v15, v250
	v_mul_f32_e32 v16, v16, v250
	v_mul_f32_e32 v17, v17, v250
	v_mul_f32_e32 v18, v18, v250
	v_mul_f32_e32 v19, v19, v250
	v_mul_f32_e32 v20, v20, v250
	v_mul_f32_e32 v21, v21, v250
	v_mul_f32_e32 v22, v22, v250
	v_mul_f32_e32 v23, v23, v250
	v_mul_f32_e32 v24, v24, v250
	v_mul_f32_e32 v25, v25, v250
	v_mul_f32_e32 v26, v26, v250
	v_mul_f32_e32 v27, v27, v250
	v_mul_f32_e32 v28, v28, v250
	v_mul_f32_e32 v29, v29, v250
	v_mul_f32_e32 v30, v30, v250
	v_mul_f32_e32 v31, v31, v250
	v_mul_f32_e32 v32, v32, v250
	v_mul_f32_e32 v33, v33, v250
	v_mul_f32_e32 v34, v34, v250
	v_mul_f32_e32 v35, v35, v250
	v_mul_f32_e32 v36, v36, v250
	v_mul_f32_e32 v37, v37, v250
	v_mul_f32_e32 v38, v38, v250
	v_mul_f32_e32 v39, v39, v250
	v_mul_f32_e32 v40, v40, v250
	v_mul_f32_e32 v41, v41, v250
	v_mul_f32_e32 v42, v42, v250
	v_mul_f32_e32 v43, v43, v250
	v_mul_f32_e32 v44, v44, v250
	v_mul_f32_e32 v45, v45, v250
	v_mul_f32_e32 v46, v46, v250
	v_mul_f32_e32 v47, v47, v250
	v_mul_f32_e32 v48, v48, v250
	v_mul_f32_e32 v49, v49, v250
	v_mul_f32_e32 v50, v50, v250
	v_mul_f32_e32 v51, v51, v250
	v_mul_f32_e32 v52, v52, v250
	v_mul_f32_e32 v53, v53, v250
	v_mul_f32_e32 v54, v54, v250
	v_mul_f32_e32 v55, v55, v250
	v_mul_f32_e32 v56, v56, v250
	v_mul_f32_e32 v57, v57, v250
	v_mul_f32_e32 v58, v58, v250
	v_mul_f32_e32 v59, v59, v250
	v_mul_f32_e32 v60, v60, v250
	v_mul_f32_e32 v61, v61, v250
	v_mul_f32_e32 v62, v62, v250
	v_mul_f32_e32 v63, v63, v250

; __device__ __forceinline__ void cmask(f32x16&p0,f32x16&p1,int jb,int qrel,int hi){
;   const float NEG=-INFINITY; int kb=64*jb+4*hi;
;   #pragma unroll
;   for(int r=0;r<16;++r){int kv=kb+(r&3)+8*(r>>2); if(kv>qrel)p0[r]=NEG; if(kv+32>qrel)p1[r]=NEG;}
; }
.Lat_step_T3:
	v_add_u32_e32 v243, s16, v204
	ds_read_b64_tr_b16 v[214:215], v243 offset:24576
	ds_read_b64_tr_b16 v[216:217], v243 offset:25088
	v_mfma_f32_32x32x16_bf16 v[112:127], v[176:179], v[144:147], v[64:79]
	v_add_f32_e32 v245, v80, v81
	v_add_f32_e32 v245, v82, v245
	v_add_f32_e32 v245, v83, v245
	v_add_f32_e32 v245, v84, v245
	v_add_f32_e32 v245, v85, v245
	v_cvt_pk_bf16_f32 v160, v80, v81
	v_cvt_pk_bf16_f32 v161, v82, v83
	ds_read_b64_tr_b16 v[80:81], v243 offset:28672
	ds_read_b64_tr_b16 v[82:83], v243 offset:29184
	v_mfma_f32_32x32x16_bf16 v[128:143], v[180:183], v[144:147], v[64:79]
	v_add_f32_e32 v245, v86, v245
	v_add_f32_e32 v245, v87, v245
	v_add_f32_e32 v245, v88, v245
	v_add_f32_e32 v245, v89, v245
	v_cvt_pk_bf16_f32 v162, v84, v85
	v_cvt_pk_bf16_f32 v163, v86, v87
	ds_read_b64_tr_b16 v[84:85], v243 offset:25600
	ds_read_b64_tr_b16 v[86:87], v243 offset:26112
	v_mfma_f32_32x32x16_bf16 v[112:127], v[184:187], v[148:151], v[112:127]
	v_add_f32_e32 v245, v90, v245
	v_add_f32_e32 v245, v91, v245
	v_add_f32_e32 v245, v92, v245
	v_add_f32_e32 v245, v93, v245
	v_cvt_pk_bf16_f32 v164, v88, v89
	v_cvt_pk_bf16_f32 v165, v90, v91
	ds_read_b64_tr_b16 v[88:89], v243 offset:29696
	ds_read_b64_tr_b16 v[90:91], v243 offset:30208
	v_mfma_f32_32x32x16_bf16 v[128:143], v[188:191], v[148:151], v[128:143]
	v_add_f32_e32 v245, v94, v245
	v_add_f32_e32 v245, v95, v245
	v_add_f32_e32 v245, v96, v245
	v_add_f32_e32 v245, v97, v245
	v_cvt_pk_bf16_f32 v166, v92, v93
	v_cvt_pk_bf16_f32 v167, v94, v95
	ds_read_b64_tr_b16 v[92:93], v243 offset:26624
	ds_read_b64_tr_b16 v[94:95], v243 offset:27136
	v_mfma_f32_32x32x16_bf16 v[112:127], v[192:195], v[152:155], v[112:127]
	v_add_f32_e32 v245, v98, v245
	v_add_f32_e32 v245, v99, v245
	v_add_f32_e32 v245, v100, v245
	v_add_f32_e32 v245, v101, v245
	v_cvt_pk_bf16_f32 v168, v96, v97
	v_cvt_pk_bf16_f32 v169, v98, v99
	ds_read_b64_tr_b16 v[96:97], v243 offset:30720
	ds_read_b64_tr_b16 v[98:99], v243 offset:31232
	v_mfma_f32_32x32x16_bf16 v[128:143], v[196:199], v[152:155], v[128:143]
	v_add_f32_e32 v245, v102, v245
	v_add_f32_e32 v245, v103, v245
	v_add_f32_e32 v245, v104, v245
	v_add_f32_e32 v245, v105, v245
	v_cvt_pk_bf16_f32 v170, v100, v101
	v_cvt_pk_bf16_f32 v171, v102, v103
	ds_read_b64_tr_b16 v[100:101], v243 offset:27648
	ds_read_b64_tr_b16 v[102:103], v243 offset:28160
	v_mfma_f32_32x32x16_bf16 v[112:127], v[200:203], v[156:159], v[112:127]
	v_add_f32_e32 v245, v106, v245
	v_add_f32_e32 v245, v107, v245
	v_add_f32_e32 v245, v108, v245
	v_add_f32_e32 v245, v109, v245
	v_cvt_pk_bf16_f32 v172, v104, v105
	v_cvt_pk_bf16_f32 v173, v106, v107
	ds_read_b64_tr_b16 v[104:105], v243 offset:31744
	ds_read_b64_tr_b16 v[106:107], v243 offset:32256
	v_mfma_f32_32x32x16_bf16 v[128:143], v[206:209], v[156:159], v[128:143]
	v_add_f32_e32 v245, v110, v245
	v_add_f32_e32 v245, v111, v245
	v_cvt_pk_bf16_f32 v174, v108, v109
	v_cvt_pk_bf16_f32 v175, v110, v111
	v_add_f32_e32 v211, v211, v245
	v_add_u32_e32 v244, s18, v219
	s_waitcnt lgkmcnt(8)
	v_mfma_f32_32x32x16_bf16 v[0:15], v[214:217], v[160:163], v[0:15]
	v_add_u32_e32 v242, 0xffffffc0, v225
	v_cmp_gt_i32_e64 s[28:29], 0, v242
	v_cmp_gt_i32_e64 s[30:31], 1, v242
	v_cmp_gt_i32_e64 s[34:35], 2, v242
	v_cndmask_b32_e64 v112, v112, v241, s[28:29]
	v_cmp_gt_i32_e64 s[28:29], 3, v242
	v_cndmask_b32_e64 v113, v113, v241, s[30:31]
	v_cmp_gt_i32_e64 s[30:31], 8, v242
	v_cndmask_b32_e64 v114, v114, v241, s[34:35]
	v_cmp_gt_i32_e64 s[34:35], 9, v242
	ds_read_b64_tr_b16 v[214:215], v243 offset:49152
	ds_read_b64_tr_b16 v[216:217], v243 offset:49664
	v_mfma_f32_32x32x16_bf16 v[16:31], v[80:83], v[160:163], v[16:31]
	v_cndmask_b32_e64 v115, v115, v241, s[28:29]
	v_cmp_gt_i32_e64 s[28:29], 10, v242
	v_cndmask_b32_e64 v116, v116, v241, s[30:31]
	v_cmp_gt_i32_e64 s[30:31], 11, v242
	v_cndmask_b32_e64 v117, v117, v241, s[34:35]
	v_cmp_gt_i32_e64 s[34:35], 16, v242
	v_cndmask_b32_e64 v118, v118, v241, s[28:29]
	v_cmp_gt_i32_e64 s[28:29], 17, v242
	v_cndmask_b32_e64 v119, v119, v241, s[30:31]
	v_cmp_gt_i32_e64 s[30:31], 18, v242
	ds_read_b64_tr_b16 v[80:81], v243 offset:53248
	ds_read_b64_tr_b16 v[82:83], v243 offset:53760
	v_mfma_f32_32x32x16_bf16 v[0:15], v[84:87], v[164:167], v[0:15]
	s_add_i32 s21, s18, s54
	s_add_i32 m0, s21, 0x6000
	v_cndmask_b32_e64 v120, v120, v241, s[34:35]
	v_cmp_gt_i32_e64 s[34:35], 19, v242
	v_cndmask_b32_e64 v121, v121, v241, s[28:29]
	v_cmp_gt_i32_e64 s[28:29], 24, v242
	v_cndmask_b32_e64 v122, v122, v241, s[30:31]
	v_cmp_gt_i32_e64 s[30:31], 25, v242
	v_cndmask_b32_e64 v123, v123, v241, s[34:35]
	v_cmp_gt_i32_e64 s[34:35], 26, v242
	v_cndmask_b32_e64 v124, v124, v241, s[28:29]
	v_cmp_gt_i32_e64 s[28:29], 27, v242
	ds_read_b64_tr_b16 v[84:85], v243 offset:50176
	ds_read_b64_tr_b16 v[86:87], v243 offset:50688
	global_load_lds_dwordx4 v223, s[4:5]
	v_mfma_f32_32x32x16_bf16 v[16:31], v[88:91], v[164:167], v[16:31]
	s_add_i32 m0, s21, 0xc000
	v_cndmask_b32_e64 v125, v125, v241, s[30:31]
	v_cmp_gt_i32_e64 s[30:31], 32, v242
	v_cndmask_b32_e64 v126, v126, v241, s[34:35]
	v_cmp_gt_i32_e64 s[34:35], 33, v242
	v_cndmask_b32_e64 v127, v127, v241, s[28:29]
	v_cmp_gt_i32_e64 s[28:29], 34, v242
	v_cndmask_b32_e64 v128, v128, v241, s[30:31]
	v_cmp_gt_i32_e64 s[30:31], 35, v242
	v_cndmask_b32_e64 v129, v129, v241, s[34:35]
	v_cmp_gt_i32_e64 s[34:35], 40, v242
	ds_read_b64_tr_b16 v[88:89], v243 offset:54272
	ds_read_b64_tr_b16 v[90:91], v243 offset:54784
	global_load_lds_dwordx4 v224, s[4:5]
	s_add_u32 s4, s4, 0x20000
	s_addc_u32 s5, s5, 0
	s_waitcnt lgkmcnt(8)
	v_mfma_f32_32x32x16_bf16 v[0:15], v[92:95], v[168:171], v[0:15]
	v_cndmask_b32_e64 v130, v130, v241, s[28:29]
	v_cmp_gt_i32_e64 s[28:29], 41, v242
	v_cndmask_b32_e64 v131, v131, v241, s[30:31]
	v_cmp_gt_i32_e64 s[30:31], 42, v242
	v_cndmask_b32_e64 v132, v132, v241, s[34:35]
	v_cmp_gt_i32_e64 s[34:35], 43, v242
	v_cndmask_b32_e64 v133, v133, v241, s[28:29]
	v_cmp_gt_i32_e64 s[28:29], 48, v242
	v_cndmask_b32_e64 v134, v134, v241, s[30:31]
	v_cmp_gt_i32_e64 s[30:31], 49, v242
	ds_read_b64_tr_b16 v[92:93], v243 offset:51200
	ds_read_b64_tr_b16 v[94:95], v243 offset:51712
	v_mfma_f32_32x32x16_bf16 v[16:31], v[96:99], v[168:171], v[16:31]
	v_cndmask_b32_e64 v135, v135, v241, s[34:35]
	v_cmp_gt_i32_e64 s[34:35], 50, v242
	v_cndmask_b32_e64 v136, v136, v241, s[28:29]
	v_cmp_gt_i32_e64 s[28:29], 51, v242
	v_cndmask_b32_e64 v137, v137, v241, s[30:31]
	v_cmp_gt_i32_e64 s[30:31], 56, v242
	v_cndmask_b32_e64 v138, v138, v241, s[34:35]
	v_cmp_gt_i32_e64 s[34:35], 57, v242
	v_cndmask_b32_e64 v139, v139, v241, s[28:29]
	v_cmp_gt_i32_e64 s[28:29], 58, v242
	ds_read_b64_tr_b16 v[96:97], v243 offset:55296
	ds_read_b64_tr_b16 v[98:99], v243 offset:55808
	v_mfma_f32_32x32x16_bf16 v[0:15], v[100:103], v[172:175], v[0:15]
	v_cndmask_b32_e64 v140, v140, v241, s[30:31]
	v_cmp_gt_i32_e64 s[30:31], 59, v242
	v_cndmask_b32_e64 v141, v141, v241, s[34:35]
	v_cndmask_b32_e64 v142, v142, v241, s[28:29]
	v_cndmask_b32_e64 v143, v143, v241, s[30:31]
	v_max3_f32 v246, v112, v113, v114
	v_max3_f32 v247, v115, v116, v117
	v_max3_f32 v246, v246, v118, v119
	v_max3_f32 v247, v247, v120, v121
	v_max3_f32 v246, v246, v122, v123
	ds_read_b64_tr_b16 v[100:101], v243 offset:52224
	ds_read_b64_tr_b16 v[102:103], v243 offset:52736
	v_mfma_f32_32x32x16_bf16 v[16:31], v[104:107], v[172:175], v[16:31]
	v_max3_f32 v247, v247, v124, v125
	v_max3_f32 v246, v246, v126, v127
	v_max3_f32 v247, v247, v128, v129
	v_max3_f32 v246, v246, v130, v131
	v_max3_f32 v247, v247, v132, v133
	v_max3_f32 v246, v246, v134, v135
	v_max3_f32 v247, v247, v136, v137
	v_max3_f32 v246, v246, v138, v139
	v_max3_f32 v247, v247, v140, v141
	v_max3_f32 v246, v246, v142, v143
	ds_read_b64_tr_b16 v[104:105], v243 offset:56320
	ds_read_b64_tr_b16 v[106:107], v243 offset:56832
	s_waitcnt lgkmcnt(8)
	v_mfma_f32_32x32x16_bf16 v[32:47], v[214:217], v[160:163], v[32:47]
	v_max_f32_e32 v248, v246, v247
	v_mov_b32_e32 v246, v248
	s_nop 1
	v_permlane32_swap_b32_e32 v248, v246
	v_max_f32_e32 v248, v248, v246
	ds_read_b128 v[176:179], v244 offset:0
	ds_read_b128 v[180:183], v244 offset:512
	v_cmp_lt_f32_e32 vcc, s87, v248
	s_cbranch_vccnz .Lat_rare_T3
.Lat_cont_T3:
	v_mfma_f32_32x32x16_bf16 v[48:63], v[80:83], v[160:163], v[48:63]
	v_exp_f32_e32 v112, v112
	v_exp_f32_e32 v113, v113
	v_exp_f32_e32 v114, v114
	v_exp_f32_e32 v115, v115
	v_exp_f32_e32 v116, v116
	ds_read_b128 v[184:187], v244 offset:2048
	ds_read_b128 v[188:191], v244 offset:2560
	v_mfma_f32_32x32x16_bf16 v[32:47], v[84:87], v[164:167], v[32:47]
	v_exp_f32_e32 v117, v117
	v_exp_f32_e32 v118, v118
	v_exp_f32_e32 v119, v119
	v_exp_f32_e32 v120, v120
	v_exp_f32_e32 v121, v121
	ds_read_b128 v[192:195], v244 offset:4096
	ds_read_b128 v[196:199], v244 offset:4608
	v_mfma_f32_32x32x16_bf16 v[48:63], v[88:91], v[164:167], v[48:63]
	v_exp_f32_e32 v122, v122
	v_exp_f32_e32 v123, v123
	v_exp_f32_e32 v124, v124
	v_exp_f32_e32 v125, v125
	v_exp_f32_e32 v126, v126
	ds_read_b128 v[200:203], v244 offset:6144
	ds_read_b128 v[206:209], v244 offset:6656
	s_waitcnt lgkmcnt(8)
	v_mfma_f32_32x32x16_bf16 v[32:47], v[92:95], v[168:171], v[32:47]
	v_exp_f32_e32 v127, v127
	v_exp_f32_e32 v128, v128
	v_exp_f32_e32 v129, v129
	v_exp_f32_e32 v130, v130
	v_exp_f32_e32 v131, v131
	v_mfma_f32_32x32x16_bf16 v[48:63], v[96:99], v[168:171], v[48:63]
	v_exp_f32_e32 v132, v132
	v_exp_f32_e32 v133, v133
	v_exp_f32_e32 v134, v134
	v_exp_f32_e32 v135, v135
	v_mfma_f32_32x32x16_bf16 v[32:47], v[100:103], v[172:175], v[32:47]
	v_exp_f32_e32 v136, v136
	v_exp_f32_e32 v137, v137
	v_exp_f32_e32 v138, v138
	v_exp_f32_e32 v139, v139
	v_mfma_f32_32x32x16_bf16 v[48:63], v[104:107], v[172:175], v[48:63]
	v_exp_f32_e32 v140, v140
	v_exp_f32_e32 v141, v141
	v_exp_f32_e32 v142, v142
	v_exp_f32_e32 v143, v143
	s_waitcnt vmcnt(2) lgkmcnt(0)
	s_barrier
	s_cbranch_vccz .Lat_noresc_T3
	v_mul_f32_e32 v0, v0, v250
	v_mul_f32_e32 v1, v1, v250
	v_mul_f32_e32 v2, v2, v250
	v_mul_f32_e32 v3, v3, v250
	v_mul_f32_e32 v4, v4, v250
	v_mul_f32_e32 v5, v5, v250
	v_mul_f32_e32 v6, v6, v250
	v_mul_f32_e32 v7, v7, v250
	v_mul_f32_e32 v8, v8, v250
	v_mul_f32_e32 v9, v9, v250
	v_mul_f32_e32 v10, v10, v250
	v_mul_f32_e32 v11, v11, v250
	v_mul_f32_e32 v12, v12, v250
	v_mul_f32_e32 v13, v13, v250
	v_mul_f32_e32 v14, v14, v250
	v_mul_f32_e32 v15, v15, v250
	v_mul_f32_e32 v16, v16, v250
	v_mul_f32_e32 v17, v17, v250
	v_mul_f32_e32 v18, v18, v250
	v_mul_f32_e32 v19, v19, v250
	v_mul_f32_e32 v20, v20, v250
	v_mul_f32_e32 v21, v21, v250
	v_mul_f32_e32 v22, v22, v250
	v_mul_f32_e32 v23, v23, v250
	v_mul_f32_e32 v24, v24, v250
	v_mul_f32_e32 v25, v25, v250
	v_mul_f32_e32 v26, v26, v250
	v_mul_f32_e32 v27, v27, v250
	v_mul_f32_e32 v28, v28, v250
	v_mul_f32_e32 v29, v29, v250
	v_mul_f32_e32 v30, v30, v250
	v_mul_f32_e32 v31, v31, v250
	v_mul_f32_e32 v32, v32, v250
	v_mul_f32_e32 v33, v33, v250
	v_mul_f32_e32 v34, v34, v250
	v_mul_f32_e32 v35, v35, v250
	v_mul_f32_e32 v36, v36, v250
	v_mul_f32_e32 v37, v37, v250
	v_mul_f32_e32 v38, v38, v250
	v_mul_f32_e32 v39, v39, v250
	v_mul_f32_e32 v40, v40, v250
	v_mul_f32_e32 v41, v41, v250
	v_mul_f32_e32 v42, v42, v250
	v_mul_f32_e32 v43, v43, v250
	v_mul_f32_e32 v44, v44, v250
	v_mul_f32_e32 v45, v45, v250
	v_mul_f32_e32 v46, v46, v250
	v_mul_f32_e32 v47, v47, v250
	v_mul_f32_e32 v48, v48, v250
	v_mul_f32_e32 v49, v49, v250
	v_mul_f32_e32 v50, v50, v250
	v_mul_f32_e32 v51, v51, v250
	v_mul_f32_e32 v52, v52, v250
	v_mul_f32_e32 v53, v53, v250
	v_mul_f32_e32 v54, v54, v250
	v_mul_f32_e32 v55, v55, v250
	v_mul_f32_e32 v56, v56, v250
	v_mul_f32_e32 v57, v57, v250
	v_mul_f32_e32 v58, v58, v250
	v_mul_f32_e32 v59, v59, v250
	v_mul_f32_e32 v60, v60, v250
	v_mul_f32_e32 v61, v61, v250
	v_mul_f32_e32 v62, v62, v250
	v_mul_f32_e32 v63, v63, v250

; __device__ __forceinline__ void cmask(f32x16&p0,f32x16&p1,int jb,int qrel,int hi){
;   const float NEG=-INFINITY; int kb=64*jb+4*hi;
;   #pragma unroll
;   for(int r=0;r<16;++r){int kv=kb+(r&3)+8*(r>>2); if(kv>qrel)p0[r]=NEG; if(kv+32>qrel)p1[r]=NEG;}
; }
.Lat_step_T2:
	v_add_u32_e32 v243, s16, v204
	ds_read_b64_tr_b16 v[214:215], v243 offset:24576
	ds_read_b64_tr_b16 v[216:217], v243 offset:25088
	v_mfma_f32_32x32x16_bf16 v[80:95], v[176:179], v[144:147], v[64:79]
	v_add_f32_e32 v245, v112, v113
	v_add_f32_e32 v245, v114, v245
	v_add_f32_e32 v245, v115, v245
	v_add_f32_e32 v245, v116, v245
	v_add_f32_e32 v245, v117, v245
	v_cvt_pk_bf16_f32 v160, v112, v113
	v_cvt_pk_bf16_f32 v161, v114, v115
	ds_read_b64_tr_b16 v[112:113], v243 offset:28672
	ds_read_b64_tr_b16 v[114:115], v243 offset:29184
	v_mfma_f32_32x32x16_bf16 v[96:111], v[180:183], v[144:147], v[64:79]
	v_add_f32_e32 v245, v118, v245
	v_add_f32_e32 v245, v119, v245
	v_add_f32_e32 v245, v120, v245
	v_add_f32_e32 v245, v121, v245
	v_cvt_pk_bf16_f32 v162, v116, v117
	v_cvt_pk_bf16_f32 v163, v118, v119
	ds_read_b64_tr_b16 v[116:117], v243 offset:25600
	ds_read_b64_tr_b16 v[118:119], v243 offset:26112
	v_mfma_f32_32x32x16_bf16 v[80:95], v[184:187], v[148:151], v[80:95]
	v_add_f32_e32 v245, v122, v245
	v_add_f32_e32 v245, v123, v245
	v_add_f32_e32 v245, v124, v245
	v_add_f32_e32 v245, v125, v245
	v_cvt_pk_bf16_f32 v164, v120, v121
	v_cvt_pk_bf16_f32 v165, v122, v123
	ds_read_b64_tr_b16 v[120:121], v243 offset:29696
	ds_read_b64_tr_b16 v[122:123], v243 offset:30208
	v_mfma_f32_32x32x16_bf16 v[96:111], v[188:191], v[148:151], v[96:111]
	v_add_f32_e32 v245, v126, v245
	v_add_f32_e32 v245, v127, v245
	v_add_f32_e32 v245, v128, v245
	v_add_f32_e32 v245, v129, v245
	v_cvt_pk_bf16_f32 v166, v124, v125
	v_cvt_pk_bf16_f32 v167, v126, v127
	ds_read_b64_tr_b16 v[124:125], v243 offset:26624
	ds_read_b64_tr_b16 v[126:127], v243 offset:27136
	v_mfma_f32_32x32x16_bf16 v[80:95], v[192:195], v[152:155], v[80:95]
	v_add_f32_e32 v245, v130, v245
	v_add_f32_e32 v245, v131, v245
	v_add_f32_e32 v245, v132, v245
	v_add_f32_e32 v245, v133, v245
	v_cvt_pk_bf16_f32 v168, v128, v129
	v_cvt_pk_bf16_f32 v169, v130, v131
	ds_read_b64_tr_b16 v[128:129], v243 offset:30720
	ds_read_b64_tr_b16 v[130:131], v243 offset:31232
	v_mfma_f32_32x32x16_bf16 v[96:111], v[196:199], v[152:155], v[96:111]
	v_add_f32_e32 v245, v134, v245
	v_add_f32_e32 v245, v135, v245
	v_add_f32_e32 v245, v136, v245
	v_add_f32_e32 v245, v137, v245
	v_cvt_pk_bf16_f32 v170, v132, v133
	v_cvt_pk_bf16_f32 v171, v134, v135
	ds_read_b64_tr_b16 v[132:133], v243 offset:27648
	ds_read_b64_tr_b16 v[134:135], v243 offset:28160
	v_mfma_f32_32x32x16_bf16 v[80:95], v[200:203], v[156:159], v[80:95]
	v_add_f32_e32 v245, v138, v245
	v_add_f32_e32 v245, v139, v245
	v_add_f32_e32 v245, v140, v245
	v_add_f32_e32 v245, v141, v245
	v_cvt_pk_bf16_f32 v172, v136, v137
	v_cvt_pk_bf16_f32 v173, v138, v139
	ds_read_b64_tr_b16 v[136:137], v243 offset:31744
	ds_read_b64_tr_b16 v[138:139], v243 offset:32256
	v_mfma_f32_32x32x16_bf16 v[96:111], v[206:209], v[156:159], v[96:111]
	v_add_f32_e32 v245, v142, v245
	v_add_f32_e32 v245, v143, v245
	v_cvt_pk_bf16_f32 v174, v140, v141
	v_cvt_pk_bf16_f32 v175, v142, v143
	v_add_f32_e32 v211, v211, v245
	v_add_u32_e32 v244, s18, v219
	s_waitcnt lgkmcnt(8)
	v_mfma_f32_32x32x16_bf16 v[0:15], v[214:217], v[160:163], v[0:15]
	v_add_u32_e32 v242, 0xffffff80, v225
	v_cmp_gt_i32_e64 s[28:29], 0, v242
	v_cmp_gt_i32_e64 s[30:31], 1, v242
	v_cmp_gt_i32_e64 s[34:35], 2, v242
	v_cndmask_b32_e64 v80, v80, v241, s[28:29]
	v_cmp_gt_i32_e64 s[28:29], 3, v242
	v_cndmask_b32_e64 v81, v81, v241, s[30:31]
	v_cmp_gt_i32_e64 s[30:31], 8, v242
	v_cndmask_b32_e64 v82, v82, v241, s[34:35]
	v_cmp_gt_i32_e64 s[34:35], 9, v242
	ds_read_b64_tr_b16 v[214:215], v243 offset:49152
	ds_read_b64_tr_b16 v[216:217], v243 offset:49664
	v_mfma_f32_32x32x16_bf16 v[16:31], v[112:115], v[160:163], v[16:31]
	v_cndmask_b32_e64 v83, v83, v241, s[28:29]
	v_cmp_gt_i32_e64 s[28:29], 10, v242
	v_cndmask_b32_e64 v84, v84, v241, s[30:31]
	v_cmp_gt_i32_e64 s[30:31], 11, v242
	v_cndmask_b32_e64 v85, v85, v241, s[34:35]
	v_cmp_gt_i32_e64 s[34:35], 16, v242
	v_cndmask_b32_e64 v86, v86, v241, s[28:29]
	v_cmp_gt_i32_e64 s[28:29], 17, v242
	v_cndmask_b32_e64 v87, v87, v241, s[30:31]
	v_cmp_gt_i32_e64 s[30:31], 18, v242
	ds_read_b64_tr_b16 v[112:113], v243 offset:53248
	ds_read_b64_tr_b16 v[114:115], v243 offset:53760
	v_mfma_f32_32x32x16_bf16 v[0:15], v[116:119], v[164:167], v[0:15]
	s_add_i32 s21, s18, s54
	s_add_i32 m0, s21, 0x6000
	v_cndmask_b32_e64 v88, v88, v241, s[34:35]
	v_cmp_gt_i32_e64 s[34:35], 19, v242
	v_cndmask_b32_e64 v89, v89, v241, s[28:29]
	v_cmp_gt_i32_e64 s[28:29], 24, v242
	v_cndmask_b32_e64 v90, v90, v241, s[30:31]
	v_cmp_gt_i32_e64 s[30:31], 25, v242
	v_cndmask_b32_e64 v91, v91, v241, s[34:35]
	v_cmp_gt_i32_e64 s[34:35], 26, v242
	v_cndmask_b32_e64 v92, v92, v241, s[28:29]
	v_cmp_gt_i32_e64 s[28:29], 27, v242
	ds_read_b64_tr_b16 v[116:117], v243 offset:50176
	ds_read_b64_tr_b16 v[118:119], v243 offset:50688
	global_load_lds_dwordx4 v223, s[4:5]
	v_mfma_f32_32x32x16_bf16 v[16:31], v[120:123], v[164:167], v[16:31]
	s_add_i32 m0, s21, 0xc000
	v_cndmask_b32_e64 v93, v93, v241, s[30:31]
	v_cmp_gt_i32_e64 s[30:31], 32, v242
	v_cndmask_b32_e64 v94, v94, v241, s[34:35]
	v_cmp_gt_i32_e64 s[34:35], 33, v242
	v_cndmask_b32_e64 v95, v95, v241, s[28:29]
	v_cmp_gt_i32_e64 s[28:29], 34, v242
	v_cndmask_b32_e64 v96, v96, v241, s[30:31]
	v_cmp_gt_i32_e64 s[30:31], 35, v242
	v_cndmask_b32_e64 v97, v97, v241, s[34:35]
	v_cmp_gt_i32_e64 s[34:35], 40, v242
	ds_read_b64_tr_b16 v[120:121], v243 offset:54272
	ds_read_b64_tr_b16 v[122:123], v243 offset:54784
	global_load_lds_dwordx4 v224, s[4:5]
	s_add_u32 s4, s4, 0x20000
	s_addc_u32 s5, s5, 0
	s_waitcnt lgkmcnt(8)
	v_mfma_f32_32x32x16_bf16 v[0:15], v[124:127], v[168:171], v[0:15]
	v_cndmask_b32_e64 v98, v98, v241, s[28:29]
	v_cmp_gt_i32_e64 s[28:29], 41, v242
	v_cndmask_b32_e64 v99, v99, v241, s[30:31]
	v_cmp_gt_i32_e64 s[30:31], 42, v242
	v_cndmask_b32_e64 v100, v100, v241, s[34:35]
	v_cmp_gt_i32_e64 s[34:35], 43, v242
	v_cndmask_b32_e64 v101, v101, v241, s[28:29]
	v_cmp_gt_i32_e64 s[28:29], 48, v242
	v_cndmask_b32_e64 v102, v102, v241, s[30:31]
	v_cmp_gt_i32_e64 s[30:31], 49, v242
	ds_read_b64_tr_b16 v[124:125], v243 offset:51200
	ds_read_b64_tr_b16 v[126:127], v243 offset:51712
	v_mfma_f32_32x32x16_bf16 v[16:31], v[128:131], v[168:171], v[16:31]
	v_cndmask_b32_e64 v103, v103, v241, s[34:35]
	v_cmp_gt_i32_e64 s[34:35], 50, v242
	v_cndmask_b32_e64 v104, v104, v241, s[28:29]
	v_cmp_gt_i32_e64 s[28:29], 51, v242
	v_cndmask_b32_e64 v105, v105, v241, s[30:31]
	v_cmp_gt_i32_e64 s[30:31], 56, v242
	v_cndmask_b32_e64 v106, v106, v241, s[34:35]
	v_cmp_gt_i32_e64 s[34:35], 57, v242
	v_cndmask_b32_e64 v107, v107, v241, s[28:29]
	v_cmp_gt_i32_e64 s[28:29], 58, v242
	ds_read_b64_tr_b16 v[128:129], v243 offset:55296
	ds_read_b64_tr_b16 v[130:131], v243 offset:55808
	v_mfma_f32_32x32x16_bf16 v[0:15], v[132:135], v[172:175], v[0:15]
	v_cndmask_b32_e64 v108, v108, v241, s[30:31]
	v_cmp_gt_i32_e64 s[30:31], 59, v242
	v_cndmask_b32_e64 v109, v109, v241, s[34:35]
	v_cndmask_b32_e64 v110, v110, v241, s[28:29]
	v_cndmask_b32_e64 v111, v111, v241, s[30:31]
	v_max3_f32 v246, v80, v81, v82
	v_max3_f32 v247, v83, v84, v85
	v_max3_f32 v246, v246, v86, v87
	v_max3_f32 v247, v247, v88, v89
	v_max3_f32 v246, v246, v90, v91
	ds_read_b64_tr_b16 v[132:133], v243 offset:52224
	ds_read_b64_tr_b16 v[134:135], v243 offset:52736
	v_mfma_f32_32x32x16_bf16 v[16:31], v[136:139], v[172:175], v[16:31]
	v_max3_f32 v247, v247, v92, v93
	v_max3_f32 v246, v246, v94, v95
	v_max3_f32 v247, v247, v96, v97
	v_max3_f32 v246, v246, v98, v99
	v_max3_f32 v247, v247, v100, v101
	v_max3_f32 v246, v246, v102, v103
	v_max3_f32 v247, v247, v104, v105
	v_max3_f32 v246, v246, v106, v107
	v_max3_f32 v247, v247, v108, v109
	v_max3_f32 v246, v246, v110, v111
	ds_read_b64_tr_b16 v[136:137], v243 offset:56320
	ds_read_b64_tr_b16 v[138:139], v243 offset:56832
	s_waitcnt lgkmcnt(8)
	v_mfma_f32_32x32x16_bf16 v[32:47], v[214:217], v[160:163], v[32:47]
	v_max_f32_e32 v248, v246, v247
	v_mov_b32_e32 v246, v248
	s_nop 1
	v_permlane32_swap_b32_e32 v248, v246
	v_max_f32_e32 v248, v248, v246
	ds_read_b128 v[176:179], v244 offset:0
	ds_read_b128 v[180:183], v244 offset:512
	v_cmp_lt_f32_e32 vcc, s87, v248
	s_cbranch_vccnz .Lat_rare_T2
.Lat_cont_T2:
	v_mfma_f32_32x32x16_bf16 v[48:63], v[112:115], v[160:163], v[48:63]
	v_exp_f32_e32 v80, v80
	v_exp_f32_e32 v81, v81
	v_exp_f32_e32 v82, v82
	v_exp_f32_e32 v83, v83
	v_exp_f32_e32 v84, v84
	ds_read_b128 v[184:187], v244 offset:2048
	ds_read_b128 v[188:191], v244 offset:2560
	v_mfma_f32_32x32x16_bf16 v[32:47], v[116:119], v[164:167], v[32:47]
	v_exp_f32_e32 v85, v85
	v_exp_f32_e32 v86, v86
	v_exp_f32_e32 v87, v87
	v_exp_f32_e32 v88, v88
	v_exp_f32_e32 v89, v89
	ds_read_b128 v[192:195], v244 offset:4096
	ds_read_b128 v[196:199], v244 offset:4608
	v_mfma_f32_32x32x16_bf16 v[48:63], v[120:123], v[164:167], v[48:63]
	v_exp_f32_e32 v90, v90
	v_exp_f32_e32 v91, v91
	v_exp_f32_e32 v92, v92
	v_exp_f32_e32 v93, v93
	v_exp_f32_e32 v94, v94
	ds_read_b128 v[200:203], v244 offset:6144
	ds_read_b128 v[206:209], v244 offset:6656
	s_waitcnt lgkmcnt(8)
	v_mfma_f32_32x32x16_bf16 v[32:47], v[124:127], v[168:171], v[32:47]
	v_exp_f32_e32 v95, v95
	v_exp_f32_e32 v96, v96
	v_exp_f32_e32 v97, v97
	v_exp_f32_e32 v98, v98
	v_exp_f32_e32 v99, v99
	v_mfma_f32_32x32x16_bf16 v[48:63], v[128:131], v[168:171], v[48:63]
	v_exp_f32_e32 v100, v100
	v_exp_f32_e32 v101, v101
	v_exp_f32_e32 v102, v102
	v_exp_f32_e32 v103, v103
	v_mfma_f32_32x32x16_bf16 v[32:47], v[132:135], v[172:175], v[32:47]
	v_exp_f32_e32 v104, v104
	v_exp_f32_e32 v105, v105
	v_exp_f32_e32 v106, v106
	v_exp_f32_e32 v107, v107
	v_mfma_f32_32x32x16_bf16 v[48:63], v[136:139], v[172:175], v[48:63]
	v_exp_f32_e32 v108, v108
	v_exp_f32_e32 v109, v109
	v_exp_f32_e32 v110, v110
	v_exp_f32_e32 v111, v111
	s_waitcnt vmcnt(0) lgkmcnt(0)
	s_barrier
	s_cbranch_vccz .Lat_noresc_T2
	v_mul_f32_e32 v0, v0, v250
	v_mul_f32_e32 v1, v1, v250
	v_mul_f32_e32 v2, v2, v250
	v_mul_f32_e32 v3, v3, v250
	v_mul_f32_e32 v4, v4, v250
	v_mul_f32_e32 v5, v5, v250
	v_mul_f32_e32 v6, v6, v250
	v_mul_f32_e32 v7, v7, v250
	v_mul_f32_e32 v8, v8, v250
	v_mul_f32_e32 v9, v9, v250
	v_mul_f32_e32 v10, v10, v250
	v_mul_f32_e32 v11, v11, v250
	v_mul_f32_e32 v12, v12, v250
	v_mul_f32_e32 v13, v13, v250
	v_mul_f32_e32 v14, v14, v250
	v_mul_f32_e32 v15, v15, v250
	v_mul_f32_e32 v16, v16, v250
	v_mul_f32_e32 v17, v17, v250
	v_mul_f32_e32 v18, v18, v250
	v_mul_f32_e32 v19, v19, v250
	v_mul_f32_e32 v20, v20, v250
	v_mul_f32_e32 v21, v21, v250
	v_mul_f32_e32 v22, v22, v250
	v_mul_f32_e32 v23, v23, v250
	v_mul_f32_e32 v24, v24, v250
	v_mul_f32_e32 v25, v25, v250
	v_mul_f32_e32 v26, v26, v250
	v_mul_f32_e32 v27, v27, v250
	v_mul_f32_e32 v28, v28, v250
	v_mul_f32_e32 v29, v29, v250
	v_mul_f32_e32 v30, v30, v250
	v_mul_f32_e32 v31, v31, v250
	v_mul_f32_e32 v32, v32, v250
	v_mul_f32_e32 v33, v33, v250
	v_mul_f32_e32 v34, v34, v250
	v_mul_f32_e32 v35, v35, v250
	v_mul_f32_e32 v36, v36, v250
	v_mul_f32_e32 v37, v37, v250
	v_mul_f32_e32 v38, v38, v250
	v_mul_f32_e32 v39, v39, v250
	v_mul_f32_e32 v40, v40, v250
	v_mul_f32_e32 v41, v41, v250
	v_mul_f32_e32 v42, v42, v250
	v_mul_f32_e32 v43, v43, v250
	v_mul_f32_e32 v44, v44, v250
	v_mul_f32_e32 v45, v45, v250
	v_mul_f32_e32 v46, v46, v250
	v_mul_f32_e32 v47, v47, v250
	v_mul_f32_e32 v48, v48, v250
	v_mul_f32_e32 v49, v49, v250
	v_mul_f32_e32 v50, v50, v250
	v_mul_f32_e32 v51, v51, v250
	v_mul_f32_e32 v52, v52, v250
	v_mul_f32_e32 v53, v53, v250
	v_mul_f32_e32 v54, v54, v250
	v_mul_f32_e32 v55, v55, v250
	v_mul_f32_e32 v56, v56, v250
	v_mul_f32_e32 v57, v57, v250
	v_mul_f32_e32 v58, v58, v250
	v_mul_f32_e32 v59, v59, v250
	v_mul_f32_e32 v60, v60, v250
	v_mul_f32_e32 v61, v61, v250
	v_mul_f32_e32 v62, v62, v250
	v_mul_f32_e32 v63, v63, v250

; __device__ __forceinline__ void cmask(f32x16&p0,f32x16&p1,int jb,int qrel,int hi){
;   const float NEG=-INFINITY; int kb=64*jb+4*hi;
;   #pragma unroll
;   for(int r=0;r<16;++r){int kv=kb+(r&3)+8*(r>>2); if(kv>qrel)p0[r]=NEG; if(kv+32>qrel)p1[r]=NEG;}
; }
.Lat_step_T1:
	v_add_u32_e32 v243, s16, v204
	ds_read_b64_tr_b16 v[214:215], v243 offset:24576
	ds_read_b64_tr_b16 v[216:217], v243 offset:25088
	v_mfma_f32_32x32x16_bf16 v[112:127], v[176:179], v[144:147], v[64:79]
	v_add_f32_e32 v245, v80, v81
	v_add_f32_e32 v245, v82, v245
	v_add_f32_e32 v245, v83, v245
	v_add_f32_e32 v245, v84, v245
	v_add_f32_e32 v245, v85, v245
	v_cvt_pk_bf16_f32 v160, v80, v81
	v_cvt_pk_bf16_f32 v161, v82, v83
	ds_read_b64_tr_b16 v[80:81], v243 offset:28672
	ds_read_b64_tr_b16 v[82:83], v243 offset:29184
	v_mfma_f32_32x32x16_bf16 v[128:143], v[180:183], v[144:147], v[64:79]
	v_add_f32_e32 v245, v86, v245
	v_add_f32_e32 v245, v87, v245
	v_add_f32_e32 v245, v88, v245
	v_add_f32_e32 v245, v89, v245
	v_cvt_pk_bf16_f32 v162, v84, v85
	v_cvt_pk_bf16_f32 v163, v86, v87
	ds_read_b64_tr_b16 v[84:85], v243 offset:25600
	ds_read_b64_tr_b16 v[86:87], v243 offset:26112
	v_mfma_f32_32x32x16_bf16 v[112:127], v[184:187], v[148:151], v[112:127]
	v_add_f32_e32 v245, v90, v245
	v_add_f32_e32 v245, v91, v245
	v_add_f32_e32 v245, v92, v245
	v_add_f32_e32 v245, v93, v245
	v_cvt_pk_bf16_f32 v164, v88, v89
	v_cvt_pk_bf16_f32 v165, v90, v91
	ds_read_b64_tr_b16 v[88:89], v243 offset:29696
	ds_read_b64_tr_b16 v[90:91], v243 offset:30208
	v_mfma_f32_32x32x16_bf16 v[128:143], v[188:191], v[148:151], v[128:143]
	v_add_f32_e32 v245, v94, v245
	v_add_f32_e32 v245, v95, v245
	v_add_f32_e32 v245, v96, v245
	v_add_f32_e32 v245, v97, v245
	v_cvt_pk_bf16_f32 v166, v92, v93
	v_cvt_pk_bf16_f32 v167, v94, v95
	ds_read_b64_tr_b16 v[92:93], v243 offset:26624
	ds_read_b64_tr_b16 v[94:95], v243 offset:27136
	v_mfma_f32_32x32x16_bf16 v[112:127], v[192:195], v[152:155], v[112:127]
	v_add_f32_e32 v245, v98, v245
	v_add_f32_e32 v245, v99, v245
	v_add_f32_e32 v245, v100, v245
	v_add_f32_e32 v245, v101, v245
	v_cvt_pk_bf16_f32 v168, v96, v97
	v_cvt_pk_bf16_f32 v169, v98, v99
	ds_read_b64_tr_b16 v[96:97], v243 offset:30720
	ds_read_b64_tr_b16 v[98:99], v243 offset:31232
	v_mfma_f32_32x32x16_bf16 v[128:143], v[196:199], v[152:155], v[128:143]
	v_add_f32_e32 v245, v102, v245
	v_add_f32_e32 v245, v103, v245
	v_add_f32_e32 v245, v104, v245
	v_add_f32_e32 v245, v105, v245
	v_cvt_pk_bf16_f32 v170, v100, v101
	v_cvt_pk_bf16_f32 v171, v102, v103
	ds_read_b64_tr_b16 v[100:101], v243 offset:27648
	ds_read_b64_tr_b16 v[102:103], v243 offset:28160
	v_mfma_f32_32x32x16_bf16 v[112:127], v[200:203], v[156:159], v[112:127]
	v_add_f32_e32 v245, v106, v245
	v_add_f32_e32 v245, v107, v245
	v_add_f32_e32 v245, v108, v245
	v_add_f32_e32 v245, v109, v245
	v_cvt_pk_bf16_f32 v172, v104, v105
	v_cvt_pk_bf16_f32 v173, v106, v107
	ds_read_b64_tr_b16 v[104:105], v243 offset:31744
	ds_read_b64_tr_b16 v[106:107], v243 offset:32256
	v_mfma_f32_32x32x16_bf16 v[128:143], v[206:209], v[156:159], v[128:143]
	v_add_f32_e32 v245, v110, v245
	v_add_f32_e32 v245, v111, v245
	v_cvt_pk_bf16_f32 v174, v108, v109
	v_cvt_pk_bf16_f32 v175, v110, v111
	v_add_f32_e32 v211, v211, v245
	s_waitcnt lgkmcnt(8)
	v_mfma_f32_32x32x16_bf16 v[0:15], v[214:217], v[160:163], v[0:15]
	v_add_u32_e32 v242, 0xffffff40, v225
	v_cmp_gt_i32_e64 s[28:29], 0, v242
	v_cmp_gt_i32_e64 s[30:31], 1, v242
	v_cmp_gt_i32_e64 s[34:35], 2, v242
	v_cndmask_b32_e64 v112, v112, v241, s[28:29]
	v_cmp_gt_i32_e64 s[28:29], 3, v242
	v_cndmask_b32_e64 v113, v113, v241, s[30:31]
	v_cmp_gt_i32_e64 s[30:31], 8, v242
	v_cndmask_b32_e64 v114, v114, v241, s[34:35]
	v_cmp_gt_i32_e64 s[34:35], 9, v242
	ds_read_b64_tr_b16 v[214:215], v243 offset:49152
	ds_read_b64_tr_b16 v[216:217], v243 offset:49664
	v_mfma_f32_32x32x16_bf16 v[16:31], v[80:83], v[160:163], v[16:31]
	v_cndmask_b32_e64 v115, v115, v241, s[28:29]
	v_cmp_gt_i32_e64 s[28:29], 10, v242
	v_cndmask_b32_e64 v116, v116, v241, s[30:31]
	v_cmp_gt_i32_e64 s[30:31], 11, v242
	v_cndmask_b32_e64 v117, v117, v241, s[34:35]
	v_cmp_gt_i32_e64 s[34:35], 16, v242
	v_cndmask_b32_e64 v118, v118, v241, s[28:29]
	v_cmp_gt_i32_e64 s[28:29], 17, v242
	v_cndmask_b32_e64 v119, v119, v241, s[30:31]
	v_cmp_gt_i32_e64 s[30:31], 18, v242
	ds_read_b64_tr_b16 v[80:81], v243 offset:53248
	ds_read_b64_tr_b16 v[82:83], v243 offset:53760
	v_mfma_f32_32x32x16_bf16 v[0:15], v[84:87], v[164:167], v[0:15]
	v_cndmask_b32_e64 v120, v120, v241, s[34:35]
	v_cmp_gt_i32_e64 s[34:35], 19, v242
	v_cndmask_b32_e64 v121, v121, v241, s[28:29]
	v_cmp_gt_i32_e64 s[28:29], 24, v242
	v_cndmask_b32_e64 v122, v122, v241, s[30:31]
	v_cmp_gt_i32_e64 s[30:31], 25, v242
	v_cndmask_b32_e64 v123, v123, v241, s[34:35]
	v_cmp_gt_i32_e64 s[34:35], 26, v242
	v_cndmask_b32_e64 v124, v124, v241, s[28:29]
	v_cmp_gt_i32_e64 s[28:29], 27, v242
	ds_read_b64_tr_b16 v[84:85], v243 offset:50176
	ds_read_b64_tr_b16 v[86:87], v243 offset:50688
	v_mfma_f32_32x32x16_bf16 v[16:31], v[88:91], v[164:167], v[16:31]
	v_cndmask_b32_e64 v125, v125, v241, s[30:31]
	v_cmp_gt_i32_e64 s[30:31], 32, v242
	v_cndmask_b32_e64 v126, v126, v241, s[34:35]
	v_cmp_gt_i32_e64 s[34:35], 33, v242
	v_cndmask_b32_e64 v127, v127, v241, s[28:29]
	v_cmp_gt_i32_e64 s[28:29], 34, v242
	v_cndmask_b32_e64 v128, v128, v241, s[30:31]
	v_cmp_gt_i32_e64 s[30:31], 35, v242
	v_cndmask_b32_e64 v129, v129, v241, s[34:35]
	v_cmp_gt_i32_e64 s[34:35], 40, v242
	ds_read_b64_tr_b16 v[88:89], v243 offset:54272
	ds_read_b64_tr_b16 v[90:91], v243 offset:54784
	s_waitcnt lgkmcnt(8)
	v_mfma_f32_32x32x16_bf16 v[0:15], v[92:95], v[168:171], v[0:15]
	v_cndmask_b32_e64 v130, v130, v241, s[28:29]
	v_cmp_gt_i32_e64 s[28:29], 41, v242
	v_cndmask_b32_e64 v131, v131, v241, s[30:31]
	v_cmp_gt_i32_e64 s[30:31], 42, v242
	v_cndmask_b32_e64 v132, v132, v241, s[34:35]
	v_cmp_gt_i32_e64 s[34:35], 43, v242
	v_cndmask_b32_e64 v133, v133, v241, s[28:29]
	v_cmp_gt_i32_e64 s[28:29], 48, v242
	v_cndmask_b32_e64 v134, v134, v241, s[30:31]
	v_cmp_gt_i32_e64 s[30:31], 49, v242
	ds_read_b64_tr_b16 v[92:93], v243 offset:51200
	ds_read_b64_tr_b16 v[94:95], v243 offset:51712
	v_mfma_f32_32x32x16_bf16 v[16:31], v[96:99], v[168:171], v[16:31]
	v_cndmask_b32_e64 v135, v135, v241, s[34:35]
	v_cmp_gt_i32_e64 s[34:35], 50, v242
	v_cndmask_b32_e64 v136, v136, v241, s[28:29]
	v_cmp_gt_i32_e64 s[28:29], 51, v242
	v_cndmask_b32_e64 v137, v137, v241, s[30:31]
	v_cmp_gt_i32_e64 s[30:31], 56, v242
	v_cndmask_b32_e64 v138, v138, v241, s[34:35]
	v_cmp_gt_i32_e64 s[34:35], 57, v242
	v_cndmask_b32_e64 v139, v139, v241, s[28:29]
	v_cmp_gt_i32_e64 s[28:29], 58, v242
	ds_read_b64_tr_b16 v[96:97], v243 offset:55296
	ds_read_b64_tr_b16 v[98:99], v243 offset:55808
	v_mfma_f32_32x32x16_bf16 v[0:15], v[100:103], v[172:175], v[0:15]
	v_cndmask_b32_e64 v140, v140, v241, s[30:31]
	v_cmp_gt_i32_e64 s[30:31], 59, v242
	v_cndmask_b32_e64 v141, v141, v241, s[34:35]
	v_cndmask_b32_e64 v142, v142, v241, s[28:29]
	v_cndmask_b32_e64 v143, v143, v241, s[30:31]
	v_max3_f32 v246, v112, v113, v114
	v_max3_f32 v247, v115, v116, v117
	v_max3_f32 v246, v246, v118, v119
	v_max3_f32 v247, v247, v120, v121
	v_max3_f32 v246, v246, v122, v123
	ds_read_b64_tr_b16 v[100:101], v243 offset:52224
	ds_read_b64_tr_b16 v[102:103], v243 offset:52736
	v_mfma_f32_32x32x16_bf16 v[16:31], v[104:107], v[172:175], v[16:31]
	v_max3_f32 v247, v247, v124, v125
	v_max3_f32 v246, v246, v126, v127
	v_max3_f32 v247, v247, v128, v129
	v_max3_f32 v246, v246, v130, v131
	v_max3_f32 v247, v247, v132, v133
	v_max3_f32 v246, v246, v134, v135
	v_max3_f32 v247, v247, v136, v137
	v_max3_f32 v246, v246, v138, v139
	v_max3_f32 v247, v247, v140, v141
	v_max3_f32 v246, v246, v142, v143
	ds_read_b64_tr_b16 v[104:105], v243 offset:56320
	ds_read_b64_tr_b16 v[106:107], v243 offset:56832
	s_waitcnt lgkmcnt(8)
	v_mfma_f32_32x32x16_bf16 v[32:47], v[214:217], v[160:163], v[32:47]
	v_max_f32_e32 v248, v246, v247
	v_mov_b32_e32 v246, v248
	s_nop 1
	v_permlane32_swap_b32_e32 v248, v246
	v_max_f32_e32 v248, v248, v246
	v_cmp_lt_f32_e32 vcc, s87, v248
	s_cbranch_vccnz .Lat_rare_T1
.Lat_cont_T1:
	v_mfma_f32_32x32x16_bf16 v[48:63], v[80:83], v[160:163], v[48:63]
	v_exp_f32_e32 v112, v112
	v_exp_f32_e32 v113, v113
	v_exp_f32_e32 v114, v114
	v_exp_f32_e32 v115, v115
	v_exp_f32_e32 v116, v116
	v_mfma_f32_32x32x16_bf16 v[32:47], v[84:87], v[164:167], v[32:47]
	v_exp_f32_e32 v117, v117
	v_exp_f32_e32 v118, v118
	v_exp_f32_e32 v119, v119
	v_exp_f32_e32 v120, v120
	v_exp_f32_e32 v121, v121
	v_mfma_f32_32x32x16_bf16 v[48:63], v[88:91], v[164:167], v[48:63]
	v_exp_f32_e32 v122, v122
	v_exp_f32_e32 v123, v123
	v_exp_f32_e32 v124, v124
	v_exp_f32_e32 v125, v125
	v_exp_f32_e32 v126, v126
	s_waitcnt lgkmcnt(0)
	v_mfma_f32_32x32x16_bf16 v[32:47], v[92:95], v[168:171], v[32:47]
	v_exp_f32_e32 v127, v127
	v_exp_f32_e32 v128, v128
	v_exp_f32_e32 v129, v129
	v_exp_f32_e32 v130, v130
	v_exp_f32_e32 v131, v131
	v_mfma_f32_32x32x16_bf16 v[48:63], v[96:99], v[168:171], v[48:63]
	v_exp_f32_e32 v132, v132
	v_exp_f32_e32 v133, v133
	v_exp_f32_e32 v134, v134
	v_exp_f32_e32 v135, v135
	v_mfma_f32_32x32x16_bf16 v[32:47], v[100:103], v[172:175], v[32:47]
	v_exp_f32_e32 v136, v136
	v_exp_f32_e32 v137, v137
	v_exp_f32_e32 v138, v138
	v_exp_f32_e32 v139, v139
	v_mfma_f32_32x32x16_bf16 v[48:63], v[104:107], v[172:175], v[48:63]
	v_exp_f32_e32 v140, v140
	v_exp_f32_e32 v141, v141
	v_exp_f32_e32 v142, v142
	v_exp_f32_e32 v143, v143
	s_cbranch_vccz .Lat_noresc_T1
	v_mul_f32_e32 v0, v0, v250
	v_mul_f32_e32 v1, v1, v250
	v_mul_f32_e32 v2, v2, v250
	v_mul_f32_e32 v3, v3, v250
	v_mul_f32_e32 v4, v4, v250
	v_mul_f32_e32 v5, v5, v250
	v_mul_f32_e32 v6, v6, v250
	v_mul_f32_e32 v7, v7, v250
	v_mul_f32_e32 v8, v8, v250
	v_mul_f32_e32 v9, v9, v250
	v_mul_f32_e32 v10, v10, v250
	v_mul_f32_e32 v11, v11, v250
	v_mul_f32_e32 v12, v12, v250
	v_mul_f32_e32 v13, v13, v250
	v_mul_f32_e32 v14, v14, v250
	v_mul_f32_e32 v15, v15, v250
	v_mul_f32_e32 v16, v16, v250
	v_mul_f32_e32 v17, v17, v250
	v_mul_f32_e32 v18, v18, v250
	v_mul_f32_e32 v19, v19, v250
	v_mul_f32_e32 v20, v20, v250
	v_mul_f32_e32 v21, v21, v250
	v_mul_f32_e32 v22, v22, v250
	v_mul_f32_e32 v23, v23, v250
	v_mul_f32_e32 v24, v24, v250
	v_mul_f32_e32 v25, v25, v250
	v_mul_f32_e32 v26, v26, v250
	v_mul_f32_e32 v27, v27, v250
	v_mul_f32_e32 v28, v28, v250
	v_mul_f32_e32 v29, v29, v250
	v_mul_f32_e32 v30, v30, v250
	v_mul_f32_e32 v31, v31, v250
	v_mul_f32_e32 v32, v32, v250
	v_mul_f32_e32 v33, v33, v250
	v_mul_f32_e32 v34, v34, v250
	v_mul_f32_e32 v35, v35, v250
	v_mul_f32_e32 v36, v36, v250
	v_mul_f32_e32 v37, v37, v250
	v_mul_f32_e32 v38, v38, v250
	v_mul_f32_e32 v39, v39, v250
	v_mul_f32_e32 v40, v40, v250
	v_mul_f32_e32 v41, v41, v250
	v_mul_f32_e32 v42, v42, v250
	v_mul_f32_e32 v43, v43, v250
	v_mul_f32_e32 v44, v44, v250
	v_mul_f32_e32 v45, v45, v250
	v_mul_f32_e32 v46, v46, v250
	v_mul_f32_e32 v47, v47, v250
	v_mul_f32_e32 v48, v48, v250
	v_mul_f32_e32 v49, v49, v250
	v_mul_f32_e32 v50, v50, v250
	v_mul_f32_e32 v51, v51, v250
	v_mul_f32_e32 v52, v52, v250
	v_mul_f32_e32 v53, v53, v250
	v_mul_f32_e32 v54, v54, v250
	v_mul_f32_e32 v55, v55, v250
	v_mul_f32_e32 v56, v56, v250
	v_mul_f32_e32 v57, v57, v250
	v_mul_f32_e32 v58, v58, v250
	v_mul_f32_e32 v59, v59, v250
	v_mul_f32_e32 v60, v60, v250
	v_mul_f32_e32 v61, v61, v250
	v_mul_f32_e32 v62, v62, v250
	v_mul_f32_e32 v63, v63, v250
; #define SBAR() __builtin_amdgcn_sched_barrier(0)
;   #define PKW(P,B) cvtpk_s(P[B],P[B+1])
; __device__ __forceinline__ void pv(f32x16*o,int vb,bf16x8 pa0,bf16x8 pa1,bf16x8 pa2,bf16x8 pa3){
;   #pragma unroll
;   for(int d0=0;d0<2;++d0){s16x4 lo[4],hi[4];
;     #pragma unroll
;     for(int ks=0;ks<4;++ks){
;       asm volatile("ds_read_b64_tr_b16 %0,%1 offset:%c2":"=&v"(lo[ks]):"v"(vb),"i"(d0*4096+ks*1024):"memory");
;       asm volatile("ds_read_b64_tr_b16 %0,%1 offset:%c2":"=&v"(hi[ks]):"v"(vb),"i"(d0*4096+ks*1024+512):"memory");}
;     asm volatile("s_waitcnt lgkmcnt(0)":::"memory");SBAR();
;     ...
;     o[d0]=__builtin_amdgcn_mfma_f32_32x32x16_bf16(pa0,PK(0),o[d0],0,0,0);
;     o[d0]=__builtin_amdgcn_mfma_f32_32x32x16_bf16(pa1,PK(1),o[d0],0,0,0);
;     o[d0]=__builtin_amdgcn_mfma_f32_32x32x16_bf16(pa2,PK(2),o[d0],0,0,0);
;     o[d0]=__builtin_amdgcn_mfma_f32_32x32x16_bf16(pa3,PK(3),o[d0],0,0,0);
;     ...
;   }
; }
; template<int THRL> __device__ __forceinline__ void attn_unit(int b,int qc,int vc,int qb,const bf16*Q,const bf16*__restrict__ K,const bf16*__restrict__ V,bf16*O,char*shm,const int tid){
;     ...
;   { float sacc=pB0[0]+pB0[1]; _Pragma("unroll") for(int r=2;r<16;++r)sacc+=pB0[r]; _Pragma("unroll") for(int r=0;r<16;++r)sacc+=pB1[r]; l_reg+=sacc;
;     pw0=(u32x4){PKW(pB0,0),PKW(pB0,2),PKW(pB0,4),PKW(pB0,6)};pw1=(u32x4){PKW(pB0,8),PKW(pB0,10),PKW(pB0,12),PKW(pB0,14)};pw2=(u32x4){PKW(pB1,0),PKW(pB1,2),PKW(pB1,4),PKW(pB1,6)};pw3=(u32x4){PKW(pB1,8),PKW(pB1,10),PKW(pB1,12),PKW(pB1,14)};
;     SBAR(); pv(o,vb0+sl_cur,PAF(0),PAF(1),PAF(2),PAF(3)); }
.Lat_noresc_T1:
.Lat_drain:
	v_add_u32_e32 v243, s17, v204
	v_add_f32_e32 v245, v112, v113
	v_add_f32_e32 v245, v114, v245
	v_add_f32_e32 v245, v115, v245
	v_add_f32_e32 v245, v116, v245
	v_add_f32_e32 v245, v117, v245
	v_cvt_pk_bf16_f32 v160, v112, v113
	v_cvt_pk_bf16_f32 v161, v114, v115
	v_add_f32_e32 v245, v118, v245
	v_add_f32_e32 v245, v119, v245
	v_add_f32_e32 v245, v120, v245
	v_add_f32_e32 v245, v121, v245
	v_cvt_pk_bf16_f32 v162, v116, v117
	v_cvt_pk_bf16_f32 v163, v118, v119
	v_add_f32_e32 v245, v122, v245
	v_add_f32_e32 v245, v123, v245
	v_add_f32_e32 v245, v124, v245
	v_add_f32_e32 v245, v125, v245
	v_cvt_pk_bf16_f32 v164, v120, v121
	v_cvt_pk_bf16_f32 v165, v122, v123
	v_add_f32_e32 v245, v126, v245
	v_add_f32_e32 v245, v127, v245
	v_add_f32_e32 v245, v128, v245
	v_add_f32_e32 v245, v129, v245
	v_cvt_pk_bf16_f32 v166, v124, v125
	v_cvt_pk_bf16_f32 v167, v126, v127
	v_add_f32_e32 v245, v130, v245
	v_add_f32_e32 v245, v131, v245
	v_add_f32_e32 v245, v132, v245
	v_add_f32_e32 v245, v133, v245
	v_cvt_pk_bf16_f32 v168, v128, v129
	v_cvt_pk_bf16_f32 v169, v130, v131
	v_add_f32_e32 v245, v134, v245
	v_add_f32_e32 v245, v135, v245
	v_add_f32_e32 v245, v136, v245
	v_add_f32_e32 v245, v137, v245
	v_cvt_pk_bf16_f32 v170, v132, v133
	v_cvt_pk_bf16_f32 v171, v134, v135
	v_add_f32_e32 v245, v138, v245
	v_add_f32_e32 v245, v139, v245
	v_add_f32_e32 v245, v140, v245
	v_add_f32_e32 v245, v141, v245
	v_cvt_pk_bf16_f32 v172, v136, v137
	v_cvt_pk_bf16_f32 v173, v138, v139
	v_add_f32_e32 v245, v142, v245
	v_add_f32_e32 v245, v143, v245
	v_cvt_pk_bf16_f32 v174, v140, v141
	v_cvt_pk_bf16_f32 v175, v142, v143
	v_add_f32_e32 v211, v211, v245
	ds_read_b64_tr_b16 v[112:113], v243 offset:24576
	ds_read_b64_tr_b16 v[114:115], v243 offset:25088
	ds_read_b64_tr_b16 v[116:117], v243 offset:28672
	ds_read_b64_tr_b16 v[118:119], v243 offset:29184
	ds_read_b64_tr_b16 v[120:121], v243 offset:25600
	ds_read_b64_tr_b16 v[122:123], v243 offset:26112
	ds_read_b64_tr_b16 v[124:125], v243 offset:29696
	ds_read_b64_tr_b16 v[126:127], v243 offset:30208
	ds_read_b64_tr_b16 v[128:129], v243 offset:26624
	ds_read_b64_tr_b16 v[130:131], v243 offset:27136
	ds_read_b64_tr_b16 v[132:133], v243 offset:30720
	ds_read_b64_tr_b16 v[134:135], v243 offset:31232
	ds_read_b64_tr_b16 v[136:137], v243 offset:27648
	ds_read_b64_tr_b16 v[138:139], v243 offset:28160
	ds_read_b64_tr_b16 v[140:141], v243 offset:31744
	ds_read_b64_tr_b16 v[142:143], v243 offset:32256
	s_waitcnt lgkmcnt(14)
	v_mfma_f32_32x32x16_bf16 v[0:15], v[112:115], v[160:163], v[0:15]
	s_waitcnt lgkmcnt(12)
	v_mfma_f32_32x32x16_bf16 v[16:31], v[116:119], v[160:163], v[16:31]
	s_waitcnt lgkmcnt(10)
	v_mfma_f32_32x32x16_bf16 v[0:15], v[120:123], v[164:167], v[0:15]
	s_waitcnt lgkmcnt(8)
	v_mfma_f32_32x32x16_bf16 v[16:31], v[124:127], v[164:167], v[16:31]
	s_waitcnt lgkmcnt(6)
	v_mfma_f32_32x32x16_bf16 v[0:15], v[128:131], v[168:171], v[0:15]
	s_waitcnt lgkmcnt(4)
	v_mfma_f32_32x32x16_bf16 v[16:31], v[132:135], v[168:171], v[16:31]
	s_waitcnt lgkmcnt(2)
	v_mfma_f32_32x32x16_bf16 v[0:15], v[136:139], v[172:175], v[0:15]
	s_waitcnt lgkmcnt(0)
	v_mfma_f32_32x32x16_bf16 v[16:31], v[140:143], v[172:175], v[16:31]
	ds_read_b64_tr_b16 v[112:113], v243 offset:49152
	ds_read_b64_tr_b16 v[114:115], v243 offset:49664
	ds_read_b64_tr_b16 v[116:117], v243 offset:53248
	ds_read_b64_tr_b16 v[118:119], v243 offset:53760
	ds_read_b64_tr_b16 v[120:121], v243 offset:50176
	ds_read_b64_tr_b16 v[122:123], v243 offset:50688
	ds_read_b64_tr_b16 v[124:125], v243 offset:54272
	ds_read_b64_tr_b16 v[126:127], v243 offset:54784
	ds_read_b64_tr_b16 v[128:129], v243 offset:51200
	ds_read_b64_tr_b16 v[130:131], v243 offset:51712
	ds_read_b64_tr_b16 v[132:133], v243 offset:55296
	ds_read_b64_tr_b16 v[134:135], v243 offset:55808
	ds_read_b64_tr_b16 v[136:137], v243 offset:52224
	ds_read_b64_tr_b16 v[138:139], v243 offset:52736
	ds_read_b64_tr_b16 v[140:141], v243 offset:56320
	ds_read_b64_tr_b16 v[142:143], v243 offset:56832
	s_waitcnt lgkmcnt(14)
	v_mfma_f32_32x32x16_bf16 v[32:47], v[112:115], v[160:163], v[32:47]
	s_waitcnt lgkmcnt(12)
	v_mfma_f32_32x32x16_bf16 v[48:63], v[116:119], v[160:163], v[48:63]
	s_waitcnt lgkmcnt(10)
	v_mfma_f32_32x32x16_bf16 v[32:47], v[120:123], v[164:167], v[32:47]
	s_waitcnt lgkmcnt(8)
	v_mfma_f32_32x32x16_bf16 v[48:63], v[124:127], v[164:167], v[48:63]
	s_waitcnt lgkmcnt(6)
	v_mfma_f32_32x32x16_bf16 v[32:47], v[128:131], v[168:171], v[32:47]
	s_waitcnt lgkmcnt(4)
	v_mfma_f32_32x32x16_bf16 v[48:63], v[132:135], v[168:171], v[48:63]
	s_waitcnt lgkmcnt(2)
	v_mfma_f32_32x32x16_bf16 v[32:47], v[136:139], v[172:175], v[32:47]
	s_waitcnt lgkmcnt(0)
; __device__ __forceinline__ int crow(int r,int hi){return (r&3)+8*(r>>2)+4*hi;}
; template<int THRL> __device__ __forceinline__ void attn_unit(int b,int qc,int vc,int qb,const bf16*Q,const bf16*__restrict__ K,const bf16*__restrict__ V,bf16*O,char*shm,const int tid){
;     ...
;   {auto rr=__builtin_amdgcn_permlane32_swap(__float_as_uint(l_reg),__float_as_uint(l_reg),false,false);l_reg=__uint_as_float(rr[0])+__uint_as_float(rr[1]);}
;   if(hi==0)wsf[32+r32]=l_reg;asm volatile("s_waitcnt lgkmcnt(0)":::"memory");
;   float rli[16];
;   #pragma unroll
;   for(int r=0;r<16;++r)rli[r]=__builtin_amdgcn_rcpf(wsf[32+crow(r,hi)]);
;   bf16*Ow=O+(rowbase+q0+wid*QBLK)*DM+vc;
;   { bf16*stg=(bf16*)(shm+LDS_OST)+wid*2048;
;     #pragma unroll
;     for(int r=0;r<16;++r){const int orow=crow(r,hi);
;       #pragma unroll
;       for(int d0=0;d0<2;++d0)stg[orow*64+d0*32+r32]=__float2bfloat16(o[d0][r]*rli[r]);}
;     asm volatile("s_waitcnt lgkmcnt(0)":::"memory");
;     #pragma unroll
;     for(int i=0;i<4;++i){const int row=i*8+(lane>>3),ch=lane&7; const u32x4 v=*(const u32x4*)(stg+row*64+ch*8); ATTN_STORE16(Ow+(long)row*DM+ch*8,v);} }
	v_mfma_f32_32x32x16_bf16 v[48:63], v[140:143], v[172:175], v[48:63]
	v_mov_b32_e32 v243, v211
	s_nop 1
	v_permlane32_swap_b32_e32 v211, v243
	v_add_f32_e32 v211, v211, v243
	v_rcp_f32_e32 v211, v211
	s_nop 0
	v_mul_f32_e32 v0, v0, v211
	v_mul_f32_e32 v1, v1, v211
	v_mul_f32_e32 v2, v2, v211
	v_mul_f32_e32 v3, v3, v211
	v_mul_f32_e32 v4, v4, v211
	v_mul_f32_e32 v5, v5, v211
	v_mul_f32_e32 v6, v6, v211
	v_mul_f32_e32 v7, v7, v211
	v_mul_f32_e32 v8, v8, v211
	v_mul_f32_e32 v9, v9, v211
	v_mul_f32_e32 v10, v10, v211
	v_mul_f32_e32 v11, v11, v211
	v_mul_f32_e32 v12, v12, v211
	v_mul_f32_e32 v13, v13, v211
	v_mul_f32_e32 v14, v14, v211
	v_mul_f32_e32 v15, v15, v211
	v_mul_f32_e32 v16, v16, v211
	v_mul_f32_e32 v17, v17, v211
	v_mul_f32_e32 v18, v18, v211
	v_mul_f32_e32 v19, v19, v211
	v_mul_f32_e32 v20, v20, v211
	v_mul_f32_e32 v21, v21, v211
	v_mul_f32_e32 v22, v22, v211
	v_mul_f32_e32 v23, v23, v211
	v_mul_f32_e32 v24, v24, v211
	v_mul_f32_e32 v25, v25, v211
	v_mul_f32_e32 v26, v26, v211
	v_mul_f32_e32 v27, v27, v211
	v_mul_f32_e32 v28, v28, v211
	v_mul_f32_e32 v29, v29, v211
	v_mul_f32_e32 v30, v30, v211
	v_mul_f32_e32 v31, v31, v211
	v_mul_f32_e32 v32, v32, v211
	v_mul_f32_e32 v33, v33, v211
	v_mul_f32_e32 v34, v34, v211
	v_mul_f32_e32 v35, v35, v211
	v_mul_f32_e32 v36, v36, v211
	v_mul_f32_e32 v37, v37, v211
	v_mul_f32_e32 v38, v38, v211
	v_mul_f32_e32 v39, v39, v211
	v_mul_f32_e32 v40, v40, v211
	v_mul_f32_e32 v41, v41, v211
	v_mul_f32_e32 v42, v42, v211
	v_mul_f32_e32 v43, v43, v211
	v_mul_f32_e32 v44, v44, v211
	v_mul_f32_e32 v45, v45, v211
	v_mul_f32_e32 v46, v46, v211
	v_mul_f32_e32 v47, v47, v211
	v_mul_f32_e32 v48, v48, v211
	v_mul_f32_e32 v49, v49, v211
	v_mul_f32_e32 v50, v50, v211
	v_mul_f32_e32 v51, v51, v211
	v_mul_f32_e32 v52, v52, v211
	v_mul_f32_e32 v53, v53, v211
	v_mul_f32_e32 v54, v54, v211
	v_mul_f32_e32 v55, v55, v211
	v_mul_f32_e32 v56, v56, v211
	v_mul_f32_e32 v57, v57, v211
	v_mul_f32_e32 v58, v58, v211
	v_mul_f32_e32 v59, v59, v211
	v_mul_f32_e32 v60, v60, v211
	v_mul_f32_e32 v61, v61, v211
	v_mul_f32_e32 v62, v62, v211
	v_mul_f32_e32 v63, v63, v211
	v_cvt_pk_bf16_f32 v80, v0, v1
	v_cvt_pk_bf16_f32 v81, v2, v3
	v_cvt_pk_bf16_f32 v82, v4, v5
	v_cvt_pk_bf16_f32 v83, v6, v7
	v_cvt_pk_bf16_f32 v84, v8, v9
	v_cvt_pk_bf16_f32 v85, v10, v11
	v_cvt_pk_bf16_f32 v86, v12, v13
	v_cvt_pk_bf16_f32 v87, v14, v15
	v_cvt_pk_bf16_f32 v88, v16, v17
	v_cvt_pk_bf16_f32 v89, v18, v19
	v_cvt_pk_bf16_f32 v90, v20, v21
	v_cvt_pk_bf16_f32 v91, v22, v23
	v_cvt_pk_bf16_f32 v92, v24, v25
	v_cvt_pk_bf16_f32 v93, v26, v27
	v_cvt_pk_bf16_f32 v94, v28, v29
	v_cvt_pk_bf16_f32 v95, v30, v31
	v_cvt_pk_bf16_f32 v96, v32, v33
	v_cvt_pk_bf16_f32 v97, v34, v35
	v_cvt_pk_bf16_f32 v98, v36, v37
	v_cvt_pk_bf16_f32 v99, v38, v39
	v_cvt_pk_bf16_f32 v100, v40, v41
	v_cvt_pk_bf16_f32 v101, v42, v43
	v_cvt_pk_bf16_f32 v102, v44, v45
	v_cvt_pk_bf16_f32 v103, v46, v47
	v_cvt_pk_bf16_f32 v104, v48, v49
	v_cvt_pk_bf16_f32 v105, v50, v51
	v_cvt_pk_bf16_f32 v106, v52, v53
	v_cvt_pk_bf16_f32 v107, v54, v55
	v_cvt_pk_bf16_f32 v108, v56, v57
	v_cvt_pk_bf16_f32 v109, v58, v59
	v_cvt_pk_bf16_f32 v110, v60, v61
	v_cvt_pk_bf16_f32 v111, v62, v63
	v_permlane32_swap_b32_e32 v80, v82
	v_permlane32_swap_b32_e32 v81, v83
	v_permlane32_swap_b32_e32 v84, v86
	v_permlane32_swap_b32_e32 v85, v87
	v_permlane32_swap_b32_e32 v88, v90
	v_permlane32_swap_b32_e32 v89, v91
	v_permlane32_swap_b32_e32 v92, v94
	v_permlane32_swap_b32_e32 v93, v95
	v_permlane32_swap_b32_e32 v96, v98
	v_permlane32_swap_b32_e32 v97, v99
	v_permlane32_swap_b32_e32 v100, v102
	v_permlane32_swap_b32_e32 v101, v103
	v_permlane32_swap_b32_e32 v104, v106
	v_permlane32_swap_b32_e32 v105, v107
	v_permlane32_swap_b32_e32 v108, v110
	v_permlane32_swap_b32_e32 v109, v111
	global_store_dwordx4 v252, v[80:83], s[6:7] offset:0
	global_store_dwordx4 v252, v[84:87], s[6:7] offset:32
	global_store_dwordx4 v252, v[88:91], s[6:7] offset:64
	global_store_dwordx4 v252, v[92:95], s[6:7] offset:96
	global_store_dwordx4 v252, v[96:99], s[6:7] offset:128
	global_store_dwordx4 v252, v[100:103], s[6:7] offset:160
	global_store_dwordx4 v252, v[104:107], s[6:7] offset:192
	global_store_dwordx4 v252, v[108:111], s[6:7] offset:224
	s_waitcnt lgkmcnt(0)
	s_barrier
	s_branch .Lat_unit_done
.Lat_rare_M1:
	v_max_f32_e32 v249, 0, v248
	v_exp_f32_e64 v250, -v249
	v_add_f32_e32 v210, v210, v249
	v_xor_b32_e32 v64, 0x80000000, v210
	v_mov_b32_e32 v65, v64
	v_mov_b32_e32 v66, v64
	v_mov_b32_e32 v67, v64
	v_mov_b32_e32 v68, v64
	v_mov_b32_e32 v69, v64
	v_mov_b32_e32 v70, v64
	v_mov_b32_e32 v71, v64
	v_mov_b32_e32 v72, v64
	v_mov_b32_e32 v73, v64
	v_mov_b32_e32 v74, v64
	v_mov_b32_e32 v75, v64
	v_mov_b32_e32 v76, v64
	v_mov_b32_e32 v77, v64
	v_mov_b32_e32 v78, v64
	v_mov_b32_e32 v79, v64
	v_sub_f32_e32 v112, v112, v249
	v_sub_f32_e32 v113, v113, v249
	v_sub_f32_e32 v114, v114, v249
	v_sub_f32_e32 v115, v115, v249
	v_sub_f32_e32 v116, v116, v249
	v_sub_f32_e32 v117, v117, v249
	v_sub_f32_e32 v118, v118, v249
	v_sub_f32_e32 v119, v119, v249
	v_sub_f32_e32 v120, v120, v249
	v_sub_f32_e32 v121, v121, v249
	v_sub_f32_e32 v122, v122, v249
	v_sub_f32_e32 v123, v123, v249
	v_sub_f32_e32 v124, v124, v249
	v_sub_f32_e32 v125, v125, v249
	v_sub_f32_e32 v126, v126, v249
	v_sub_f32_e32 v127, v127, v249
	v_sub_f32_e32 v128, v128, v249
	v_sub_f32_e32 v129, v129, v249
	v_sub_f32_e32 v130, v130, v249
	v_sub_f32_e32 v131, v131, v249
	v_sub_f32_e32 v132, v132, v249
	v_sub_f32_e32 v133, v133, v249
	v_sub_f32_e32 v134, v134, v249
	v_sub_f32_e32 v135, v135, v249
	v_sub_f32_e32 v136, v136, v249
	v_sub_f32_e32 v137, v137, v249
	v_sub_f32_e32 v138, v138, v249
	v_sub_f32_e32 v139, v139, v249
	v_sub_f32_e32 v140, v140, v249
	v_sub_f32_e32 v141, v141, v249
	v_sub_f32_e32 v142, v142, v249
	v_sub_f32_e32 v143, v143, v249
	v_mul_f32_e32 v211, v211, v250
	s_branch .Lat_cont_M1
.Lat_rare_M2:
	v_max_f32_e32 v249, 0, v248
	v_exp_f32_e64 v250, -v249
	v_add_f32_e32 v210, v210, v249
	v_xor_b32_e32 v64, 0x80000000, v210
	v_mov_b32_e32 v65, v64
	v_mov_b32_e32 v66, v64
	v_mov_b32_e32 v67, v64
	v_mov_b32_e32 v68, v64
	v_mov_b32_e32 v69, v64
	v_mov_b32_e32 v70, v64
	v_mov_b32_e32 v71, v64
	v_mov_b32_e32 v72, v64
	v_mov_b32_e32 v73, v64
	v_mov_b32_e32 v74, v64
	v_mov_b32_e32 v75, v64
	v_mov_b32_e32 v76, v64
	v_mov_b32_e32 v77, v64
	v_mov_b32_e32 v78, v64
	v_mov_b32_e32 v79, v64
	v_sub_f32_e32 v80, v80, v249
	v_sub_f32_e32 v81, v81, v249
	v_sub_f32_e32 v82, v82, v249
	v_sub_f32_e32 v83, v83, v249
	v_sub_f32_e32 v84, v84, v249
	v_sub_f32_e32 v85, v85, v249
	v_sub_f32_e32 v86, v86, v249
	v_sub_f32_e32 v87, v87, v249
	v_sub_f32_e32 v88, v88, v249
	v_sub_f32_e32 v89, v89, v249
	v_sub_f32_e32 v90, v90, v249
	v_sub_f32_e32 v91, v91, v249
	v_sub_f32_e32 v92, v92, v249
	v_sub_f32_e32 v93, v93, v249
	v_sub_f32_e32 v94, v94, v249
	v_sub_f32_e32 v95, v95, v249
	v_sub_f32_e32 v96, v96, v249
	v_sub_f32_e32 v97, v97, v249
	v_sub_f32_e32 v98, v98, v249
	v_sub_f32_e32 v99, v99, v249
	v_sub_f32_e32 v100, v100, v249
	v_sub_f32_e32 v101, v101, v249
	v_sub_f32_e32 v102, v102, v249
	v_sub_f32_e32 v103, v103, v249
	v_sub_f32_e32 v104, v104, v249
	v_sub_f32_e32 v105, v105, v249
	v_sub_f32_e32 v106, v106, v249
	v_sub_f32_e32 v107, v107, v249
	v_sub_f32_e32 v108, v108, v249
	v_sub_f32_e32 v109, v109, v249
	v_sub_f32_e32 v110, v110, v249
	v_sub_f32_e32 v111, v111, v249
	v_mul_f32_e32 v211, v211, v250
	s_branch .Lat_cont_M2
